# baseline (speedup 1.0000x reference)
; __device__ void phase1(const Params& p) {
;   char* ws = p.ws;
;   const u16* X = (const u16*)(ws + OFF_XH);
;   const u16* W = (const u16*)(ws + OFF_WIN);
;   const float* rs = (const float*)(ws + OFF_RS);
;   constexpr int nM = T / 256, nN = NIN / 256;
;   f32x4 acc[2][2][4][2];
;   for (int it = 0;; ++it) {
;     int pm, pn;
;     if (!tile_coords(it, nM, nN, pm, pn)) break;
;     const int to = pm * 256, fo = pn * 256;
;     gemm_tile(W, X, D, fo, to, acc);
.LBB0_152:
	v_writelane_b32 v254, s90, 2
	s_nop 1
	v_writelane_b32 v254, s91, 3
	s_or_b64 exec, exec, s[0:1]
	s_add_u32 s38, s30, 0x35000000
	s_addc_u32 s39, s31, 0
	s_add_u32 s3, s30, 0x100000
	s_addc_u32 s11, s31, 0
	s_and_b32 s4, s33, 7
	s_cmp_eq_u32 s4, 0
	s_cselect_b64 s[0:1], -1, 0
	s_cmp_lg_u32 s4, 0
	s_cselect_b64 s[36:37], -1, 0
	s_and_b32 s4, s2, 7
	s_ashr_i32 s5, s33, 3
	s_mul_i32 s35, s5, s4
	s_ashr_i32 s4, s2, 3
	s_add_i32 s35, s35, s4
	s_add_u32 s91, s30, 0x100f80
	s_addc_u32 s92, s31, 0
	s_add_u32 s46, s30, 0x21000000
	s_addc_u32 s47, s31, 0
	s_add_u32 s44, s30, 0x1c000000
	s_addc_u32 s45, s31, 0
	s_add_u32 s40, s30, 0x12000000
	s_addc_u32 s41, s31, 0
	s_add_u32 s42, s30, 0x8000000
	v_cndmask_b32_e64 v0, 0, 1, s[0:1]
	s_mov_b32 s90, 0
	s_mov_b32 s100, 0
	s_addc_u32 s43, s31, 0
	v_cmp_ne_u32_e64 s[4:5], 1, v0
	v_mov_b32_e32 v129, 0
	s_mov_b64 s[0:1], 0x80
	s_mov_b64 s[16:17], 0x180080
	s_mov_b64 s[18:19], 0x35000100
	s_mov_b64 s[20:21], 0x100100
	s_mov_b64 s[22:23], 0x35080100
	s_mov_b64 s[52:53], 0x180100
	s_mov_b64 s[56:57], 0x35000180
	s_mov_b64 s[62:63], 0x100180
	s_mov_b64 s[64:65], 0x35080180
	v_mov_b32_e32 v144, 1
	s_barrier
	s_branch .LBB0_155

; __device__ __forceinline__ int otid() { int t = threadIdx.x; asm volatile("" : "+v"(t)); return t; }
; #define WAIT_V(n) asm volatile("s_waitcnt vmcnt(" #n ")" ::: "memory")
; #define BAR __builtin_amdgcn_s_barrier()
; __device__ __forceinline__ void gemm_tile(const u16* __restrict__ A, const u16* __restrict__ Bt, const int K,
;                                           const int brow, const int bcol, f32x4 (&acc)[2][2][4][2],
;                                           const bool ZERO_INIT = true) {
;   u16* shm = reinterpret_cast<u16*>(g_smem);
;   const int tidx = otid();
;   const int wid = tidx >> 6, lane = tidx & 63, wr = wid >> 2, wc = wid & 3, fr = lane & 15, fq = lane >> 4;
;   #pragma unroll
;   for (int a = 0; a < 2; ++a)
;     #pragma unroll
;     for (int b = 0; b < 2; ++b)
;       #pragma unroll
;       for (int m = 0; m < 4; ++m)
;         #pragma unroll
;         for (int n = 0; n < 2; ++n)
;           if (ZERO_INIT) acc[a][b][m][n] = f32x4{0.f, 0.f, 0.f, 0.f};
;   bf16x8 At[4][2], B0[2][2], B1[2][2];
;   const int nt = K / BK;
;   const unsigned ldsw = (unsigned)__builtin_amdgcn_readfirstlane(wid) * 1024u;
;   unsigned vo0, vo1;
;   {
;     int r0, c0, r1, c1;
;     stage_rc(tidx * 16, r0, c0);
;     stage_rc(tidx * 16 + 8192, r1, c1);
;     vo0 = (unsigned)(r0 * K + c0) * 2u;
;     vo1 = (unsigned)(r1 * K + c1) * 2u;
;   }
;   STAGE(SB(0, 0), Bt, bcol, 0); STAGE(SA(0, 0), A, brow, 0);
;   STAGE(SB(0, 1), Bt, bcol + HALF, 0); STAGE(SA(0, 1), A, brow + HALF, 0);
;   if (wr == 1) BAR;
;   WAIT_V(4); BAR;
;   STAGE(SB(1, 0), Bt, bcol, 1); STAGE(SA(1, 0), A, brow, 1); STAGE(SB(1, 1), Bt, bcol + HALF, 1);
;   WAIT_V(6); BAR;
.LBB0_161:
	v_mov_b32_e32 v140, v194
	s_lshl_b32 s72, s93, 8
	v_bfe_i32 v1, v140, 27, 1
	v_lshlrev_b32_e32 v5, 4, v140
	v_lshrrev_b32_e32 v1, 22, v1
	v_add_u32_e32 v1, v5, v1
	v_and_b32_e32 v1, 0xfffffc00, v1
	v_sub_u32_e32 v1, v5, v1
	v_lshrrev_b32_e32 v3, 4, v1
	v_bitop3_b32 v4, v3, v1, 32 bitop3:0x6c
	v_ashrrev_i32_e32 v1, 31, v1
	v_lshrrev_b32_e32 v1, 26, v1
	v_add_u32_e32 v1, v4, v1
	v_ashrrev_i32_e32 v1, 6, v1
	v_mul_i32_i24_e32 v6, 64, v1
	v_sub_u32_e32 v4, v4, v6
	v_add_u32_e32 v6, 0x2000, v5
	v_ashrrev_i32_e32 v5, 31, v6
	v_lshrrev_b32_e32 v5, 22, v5
	v_add_u32_e32 v5, v6, v5
	v_ashrrev_i32_e32 v5, 10, v5
	v_ashrrev_i32_e32 v2, 6, v140
	v_mul_i32_i24_e32 v7, 0x400, v5
	v_readfirstlane_b32 s7, v2
	v_ashrrev_i32_e32 v0, 31, v140
	v_sub_u32_e32 v6, v6, v7
	s_ashr_i32 s73, s72, 31
	s_lshl_b32 s6, s94, 8
	s_lshl_b32 s95, s7, 10
	v_lshrrev_b32_e32 v0, 26, v0
	v_lshrrev_b32_e32 v7, 4, v6
	s_lshl_b64 s[70:71], s[72:73], 12
	v_add_u32_e32 v0, v140, v0
	v_bitop3_b32 v8, v7, v6, 32 bitop3:0x6c
	v_lshlrev_b32_e32 v6, 3, v5
	s_add_u32 s78, s38, s70
	v_ashrrev_i32_e32 v0, 6, v0
	v_and_b32_e32 v7, 0xffff0, v6
	v_ashrrev_i32_e32 v6, 31, v8
	s_addc_u32 s79, s39, s71
	s_ashr_i32 s7, s6, 31
	v_lshlrev_b32_e32 v3, 3, v0
	v_lshrrev_b32_e32 v6, 26, v6
	s_add_i32 s73, s95, 0x10000
	s_add_i32 s96, s95, 0x12000
	s_lshl_b64 s[76:77], s[6:7], 12
	v_and_b32_e32 v3, 0xffff0, v3
	v_add_u32_e32 v10, v8, v6
	s_add_u32 s80, s3, s76
	v_add_u32_e32 v9, v1, v3
	v_lshlrev_b32_e32 v3, 5, v0
	v_ashrrev_i32_e32 v6, 6, v10
	v_and_b32_e32 v10, 0xc0, v10
	s_addc_u32 s81, s11, s77
	s_or_b32 s24, s72, 0x80
	v_and_b32_e32 v3, 32, v3
	v_ashrrev_i16_sdwa v4, v144, sext(v4) dst_sel:DWORD dst_unused:UNUSED_PAD src0_sel:DWORD src1_sel:BYTE_0
	v_add_u32_e32 v11, v6, v7
	v_lshlrev_b32_e32 v7, 5, v5
	v_sub_u32_e32 v8, v8, v10
	s_ashr_i32 s25, s24, 31
	v_bfe_i32 v4, v4, 0, 16
	v_and_b32_e32 v7, 32, v7
	v_ashrrev_i16_sdwa v8, v144, sext(v8) dst_sel:DWORD dst_unused:UNUSED_PAD src0_sel:DWORD src1_sel:BYTE_0
	v_lshl_or_b32 v9, v9, 11, v3
	s_add_i32 s7, s95, 0x2000
	s_lshl_b64 s[24:25], s[24:25], 12
	v_bfe_i32 v8, v8, 0, 16
	v_add_lshl_u32 v128, v9, v4, 1
	v_lshl_or_b32 v9, v11, 11, v7
	s_add_u32 s82, s38, s24
	s_addc_u32 s83, s39, s25
	v_add_lshl_u32 v130, v9, v8, 1
	s_or_b32 s24, s6, 0x80
	s_ashr_i32 s25, s24, 31
	s_add_i32 s97, s95, 0x14000
	s_add_i32 s89, s95, 0x16000
	s_lshl_b64 s[66:67], s[24:25], 12
	s_add_u32 s84, s3, s66
	s_addc_u32 s85, s11, s67
	s_add_i32 s88, s95, 0x4000
	s_add_i32 s24, s95, 0x6000
	v_ashrrev_i32_e32 v9, 8, v140
	v_mov_b32_e32 v250, v128
	v_mov_b32_e32 v251, v130
	s_cmp_eq_u32 s100, 1
	s_cbranch_scc1 .Lp1_pf_skip
	s_mov_b32 m0, s73
	s_nop 0
	global_load_lds_dwordx4 v128, s[78:79]
	s_mov_b32 m0, s96
	s_nop 0
	global_load_lds_dwordx4 v130, s[78:79]
	s_mov_b32 m0, s95
	s_nop 0
	global_load_lds_dwordx4 v128, s[80:81]
	s_mov_b32 m0, s7
	s_nop 0
	global_load_lds_dwordx4 v130, s[80:81]
	s_mov_b32 m0, s97
	s_nop 0
	global_load_lds_dwordx4 v128, s[82:83]
	s_mov_b32 m0, s89
	s_nop 0
	global_load_lds_dwordx4 v130, s[82:83]
	s_mov_b32 m0, s88
	s_nop 0
	global_load_lds_dwordx4 v128, s[84:85]
	s_mov_b32 m0, s24
	s_nop 0
	global_load_lds_dwordx4 v130, s[84:85]
.Lp1_pf_skip:
	v_cmp_eq_u32_e32 vcc, 1, v9
	s_and_saveexec_b64 s[84:85], vcc
	s_cbranch_execz .LBB0_163
	s_barrier
.LBB0_163:
	s_or_b64 exec, exec, s[84:85]
	v_lshl_add_u64 v[10:11], s[78:79], 0, v[128:129]
	v_mov_b32_e32 v131, v129
	s_add_i32 s25, s95, 0x18000
	v_lshl_add_u64 v[12:13], s[78:79], 0, v[130:131]
	v_lshl_add_u64 v[10:11], v[10:11], 0, s[0:1]
	s_mov_b32 m0, s25
	s_add_i32 s78, s95, 0x1a000
	v_lshl_add_u64 v[14:15], s[80:81], 0, v[128:129]
	s_cmp_eq_u32 s100, 1
	s_cbranch_scc1 .Lp1_w1_pf
	s_waitcnt vmcnt(4)
	s_branch .Lp1_w1_done
.Lp1_w1_pf:
	s_cmp_eq_u32 s101, 1
	s_cbranch_scc1 .Lp1_w1_pfg
	s_waitcnt vmcnt(20)
	s_branch .Lp1_w1_done
.Lp1_w1_pfg:
	s_waitcnt vmcnt(12)
.Lp1_w1_done:
	s_barrier
	global_load_lds_dwordx4 v[10:11], off
	v_lshl_add_u64 v[10:11], v[12:13], 0, s[0:1]
	s_mov_b32 m0, s78
	s_add_i32 s79, s95, 0x8000
	v_lshl_add_u64 v[16:17], s[80:81], 0, v[130:131]
	global_load_lds_dwordx4 v[10:11], off
	v_lshl_add_u64 v[10:11], v[14:15], 0, s[0:1]
	s_mov_b32 m0, s79
	s_add_i32 s80, s95, 0xa000
	v_lshl_add_u64 v[18:19], s[82:83], 0, v[128:129]
	global_load_lds_dwordx4 v[10:11], off
	v_lshl_add_u64 v[10:11], v[16:17], 0, s[0:1]
	s_mov_b32 m0, s80
	s_add_i32 s81, s95, 0x1c000
	v_lshl_add_u64 v[20:21], s[82:83], 0, v[130:131]
	global_load_lds_dwordx4 v[10:11], off
	v_lshl_add_u64 v[10:11], v[18:19], 0, s[0:1]
	s_mov_b32 m0, s81
	s_add_i32 s82, s95, 0x1e000
	global_load_lds_dwordx4 v[10:11], off
	v_lshl_add_u64 v[10:11], v[20:21], 0, s[0:1]
	s_mov_b32 m0, s82
	v_and_b32_e32 v22, 15, v140
	global_load_lds_dwordx4 v[10:11], off
	v_lshlrev_b32_e32 v2, 12, v2
	v_and_b32_e32 v23, 48, v140
	v_and_b32_e32 v10, 0x3000, v2
	v_lshlrev_b32_e32 v2, 6, v22
	v_lshlrev_b32_e32 v12, 2, v140
	v_or_b32_e32 v11, v2, v23
	v_and_b32_e32 v12, 32, v12
	s_mov_b32 s83, 0x10000
	v_bitop3_b32 v14, v11, s83, v12 bitop3:0xde
	s_mov_b32 s83, 0x14000
	v_bitop3_b32 v13, v2, v12, v23 bitop3:0x36
	v_bitop3_b32 v15, v11, s83, v12 bitop3:0xde
	s_mov_b32 s83, 0x18000
	v_lshlrev_b32_e32 v2, 6, v140
	v_bitop3_b32 v16, v11, s83, v12 bitop3:0xde
	s_mov_b32 s83, 0x1c000
	v_and_b32_e32 v2, 0x3c0, v2
	v_lshlrev_b32_e32 v0, 14, v0
	v_bitop3_b32 v11, v11, s83, v12 bitop3:0xde
	v_bitop3_b32 v12, v2, v12, v23 bitop3:0x36
	v_and_b32_e32 v0, 0x7fff8000, v0
	v_lshlrev_b32_e32 v2, 14, v5
	v_lshl_add_u32 v0, v1, 11, v0
	v_and_b32_e32 v2, 0x7fff8000, v2
	v_or_b32_e32 v0, v0, v3
	v_lshl_add_u32 v2, v6, 11, v2
	s_cmp_eq_u32 s100, 1
	s_cbranch_scc1 .Lp1_w2_pf
	s_waitcnt vmcnt(6)
	s_branch .Lp1_w2_done
; #define WAIT_V(n) asm volatile("s_waitcnt vmcnt(" #n ")" ::: "memory")
; #define BAR __builtin_amdgcn_s_barrier()
; __device__ __forceinline__ void gemm_tile(const u16* __restrict__ A, const u16* __restrict__ Bt, const int K,
;                                           const int brow, const int bcol, f32x4 (&acc)[2][2][4][2],
;                                           const bool ZERO_INIT = true) {
;     ...
;   #pragma unroll
;   for (int a = 0; a < 2; ++a)
;     #pragma unroll
;     for (int b = 0; b < 2; ++b)
;       #pragma unroll
;       for (int m = 0; m < 4; ++m)
;         #pragma unroll
;         for (int n = 0; n < 2; ++n)
;           if (ZERO_INIT) acc[a][b][m][n] = f32x4{0.f, 0.f, 0.f, 0.f};
;   bf16x8 At[4][2], B0[2][2], B1[2][2];
;   const int nt = K / BK;
;   const unsigned ldsw = (unsigned)__builtin_amdgcn_readfirstlane(wid) * 1024u;
;   unsigned vo0, vo1;
;   {
;     int r0, c0, r1, c1;
;     stage_rc(tidx * 16, r0, c0);
;     stage_rc(tidx * 16 + 8192, r1, c1);
;     vo0 = (unsigned)(r0 * K + c0) * 2u;
;     vo1 = (unsigned)(r1 * K + c1) * 2u;
;   }
;   STAGE(SB(0, 0), Bt, bcol, 0); STAGE(SA(0, 0), A, brow, 0);
;   STAGE(SB(0, 1), Bt, bcol + HALF, 0); STAGE(SA(0, 1), A, brow + HALF, 0);
;   if (wr == 1) BAR;
;   WAIT_V(4); BAR;
;   STAGE(SB(1, 0), Bt, bcol, 1); STAGE(SA(1, 0), A, brow, 1); STAGE(SB(1, 1), Bt, bcol + HALF, 1);
;   WAIT_V(6); BAR;
.Lp1_w2_pf:
	s_cmp_eq_u32 s101, 1
	s_cbranch_scc1 .Lp1_w2_pfg
	s_waitcnt vmcnt(22)
	s_branch .Lp1_w2_done
.Lp1_w2_pfg:
	s_waitcnt vmcnt(14)
.Lp1_w2_done:
	v_lshlrev_b32_e32 v9, 13, v9
	v_add_lshl_u32 v0, v0, v4, 1
	v_mov_b32_e32 v1, v129
	v_or_b32_e32 v2, v2, v7
	v_or_b32_e32 v17, 0x800, v9
	v_or_b32_e32 v18, 0x1000, v9
	v_or_b32_e32 v19, 0x1800, v9
	v_lshl_add_u64 v[132:133], s[70:71], 0, v[0:1]
	v_add_lshl_u32 v2, v2, v8, 1
	v_mov_b32_e32 v3, v129
	v_lshl_add_u64 v[136:137], s[76:77], 0, v[0:1]
	v_mov_b32_e32 v0, 0
	v_lshl_add_u64 v[134:135], s[70:71], 0, v[2:3]
	v_lshl_add_u64 v[138:139], s[76:77], 0, v[2:3]
	s_mov_b32 s77, -2
	v_add_u32_e32 v149, v14, v10
	v_add_u32_e32 v145, v13, v9
	v_add_u32_e32 v143, v12, v17
	v_add_u32_e32 v142, v12, v18
	v_add_u32_e32 v141, v12, v19
	s_add_i32 s83, s95, 0xc000
	s_add_i32 s76, s95, 0xe000
	v_add_u32_e32 v148, v15, v10
	v_add_u32_e32 v147, v16, v10
	v_add_u32_e32 v146, v11, v10
	s_mov_b64 s[70:71], s[30:31]
	v_mov_b32_e32 v1, v0
	v_mov_b32_e32 v2, v0
	v_mov_b32_e32 v3, v0
	v_mov_b32_e32 v4, v0
	v_mov_b32_e32 v5, v0
	v_mov_b32_e32 v6, v0
	v_mov_b32_e32 v7, v0
	v_mov_b32_e32 v8, v0
	v_mov_b32_e32 v9, v0
	v_mov_b32_e32 v10, v0
	v_mov_b32_e32 v11, v0
	v_mov_b32_e32 v12, v0
	v_mov_b32_e32 v13, v0
	v_mov_b32_e32 v14, v0
	v_mov_b32_e32 v15, v0
	v_mov_b32_e32 v16, v0
	v_mov_b32_e32 v17, v0
	v_mov_b32_e32 v18, v0
	v_mov_b32_e32 v19, v0
	v_mov_b32_e32 v20, v0
	v_mov_b32_e32 v21, v0
	v_mov_b32_e32 v22, v0
	v_mov_b32_e32 v23, v0
	v_mov_b32_e32 v24, v0
	v_mov_b32_e32 v25, v0
	v_mov_b32_e32 v26, v0
	v_mov_b32_e32 v27, v0
	v_mov_b32_e32 v28, v0
	v_mov_b32_e32 v29, v0
	v_mov_b32_e32 v30, v0
	v_mov_b32_e32 v31, v0
	v_mov_b32_e32 v32, v0
	v_mov_b32_e32 v33, v0
	v_mov_b32_e32 v34, v0
	v_mov_b32_e32 v35, v0
	v_mov_b32_e32 v36, v0
	v_mov_b32_e32 v37, v0
	v_mov_b32_e32 v38, v0
	v_mov_b32_e32 v39, v0
	v_mov_b32_e32 v40, v0
	v_mov_b32_e32 v41, v0
	v_mov_b32_e32 v42, v0
	v_mov_b32_e32 v43, v0
	v_mov_b32_e32 v44, v0
	v_mov_b32_e32 v45, v0
	v_mov_b32_e32 v46, v0
	v_mov_b32_e32 v47, v0
	v_mov_b32_e32 v48, v0
	v_mov_b32_e32 v49, v0
	v_mov_b32_e32 v50, v0
	v_mov_b32_e32 v51, v0
	v_mov_b32_e32 v52, v0
	v_mov_b32_e32 v53, v0
	v_mov_b32_e32 v54, v0
	v_mov_b32_e32 v55, v0
	v_mov_b32_e32 v56, v0
	v_mov_b32_e32 v57, v0
	v_mov_b32_e32 v58, v0
	v_mov_b32_e32 v59, v0
	v_mov_b32_e32 v60, v0
	v_mov_b32_e32 v61, v0
	v_mov_b32_e32 v62, v0
	v_mov_b32_e32 v63, v0
	v_mov_b32_e32 v64, v0
	v_mov_b32_e32 v65, v0
	v_mov_b32_e32 v66, v0
	v_mov_b32_e32 v67, v0
	v_mov_b32_e32 v68, v0
	v_mov_b32_e32 v69, v0
	v_mov_b32_e32 v70, v0
	v_mov_b32_e32 v71, v0
	v_mov_b32_e32 v72, v0
	v_mov_b32_e32 v73, v0
	v_mov_b32_e32 v74, v0
	v_mov_b32_e32 v75, v0
	v_mov_b32_e32 v76, v0
	v_mov_b32_e32 v77, v0
	v_mov_b32_e32 v78, v0
	v_mov_b32_e32 v79, v0
	v_mov_b32_e32 v80, v0
	v_mov_b32_e32 v81, v0
	v_mov_b32_e32 v82, v0
	v_mov_b32_e32 v83, v0
	v_mov_b32_e32 v84, v0
	v_mov_b32_e32 v85, v0
	v_mov_b32_e32 v86, v0
	v_mov_b32_e32 v87, v0
	v_mov_b32_e32 v88, v0
	v_mov_b32_e32 v89, v0
	v_mov_b32_e32 v90, v0
	v_mov_b32_e32 v91, v0
	v_mov_b32_e32 v92, v0
	v_mov_b32_e32 v93, v0
	v_mov_b32_e32 v94, v0
	v_mov_b32_e32 v95, v0
	v_mov_b32_e32 v96, v0
	v_mov_b32_e32 v97, v0
	v_mov_b32_e32 v98, v0
	v_mov_b32_e32 v99, v0
	v_mov_b32_e32 v100, v0
	v_mov_b32_e32 v101, v0
	v_mov_b32_e32 v102, v0
	v_mov_b32_e32 v103, v0
	v_mov_b32_e32 v104, v0
	v_mov_b32_e32 v105, v0
	v_mov_b32_e32 v106, v0
	v_mov_b32_e32 v107, v0
	v_mov_b32_e32 v108, v0
	v_mov_b32_e32 v109, v0
	v_mov_b32_e32 v110, v0
	v_mov_b32_e32 v111, v0
	v_mov_b32_e32 v112, v0
	v_mov_b32_e32 v113, v0
	v_mov_b32_e32 v114, v0
	v_mov_b32_e32 v115, v0
	v_mov_b32_e32 v116, v0
	v_mov_b32_e32 v117, v0
	v_mov_b32_e32 v118, v0
	v_mov_b32_e32 v119, v0
	v_mov_b32_e32 v120, v0
	v_mov_b32_e32 v121, v0
	v_mov_b32_e32 v122, v0
	v_mov_b32_e32 v123, v0
	v_mov_b32_e32 v124, v0
	v_mov_b32_e32 v125, v0
	v_mov_b32_e32 v126, v0
	v_mov_b32_e32 v127, v0
	s_barrier

; #define EPI_BEGIN_S int fo_e = fo, to_e = to; asm volatile("" : "+s"(fo_e), "+s"(to_e));
; __device__ __forceinline__ bool tile_coords(int it, int nM, int nN, int& pm, int& pn) {
;   const int G = gridDim.x, b = blockIdx.x, ntiles = nM * nN;
;   int L;
;   if ((G & 7) == 0 && (it + 1) * G <= ntiles) L = it * G + (b & 7) * (G >> 3) + (b >> 3);
;   else L = it * G + b;
;   if (L >= ntiles) return false;
;   const int nig = 8 * nN, gid = L / nig, fm = gid * 8, gsz = min(nM - fm, 8);
;   pm = fm + (L % nig) % gsz;
;   pn = (L % nig) / gsz;
;   return true;
; }
; __device__ void phase1(const Params& p) {
;     ...
;     EPI_COORDS
;     EPI_BEGIN_S
;     u16* dst; int ld, cofs, act;
;     if (fo < 2048) { dst = (u16*)(ws + OFF_XA); ld = 2048; cofs = 0; act = 0; }
;     else if (fo < 4096) { dst = (u16*)(ws + OFF_ZA); ld = 2048; cofs = 2048; act = 1; }
;     else if (fo < 5120) { dst = (u16*)(ws + OFF_XB); ld = 1024; cofs = 4096; act = 0; }
;     else if (fo < 6144) { dst = (u16*)(ws + OFF_ZB); ld = 1024; cofs = 5120; act = 1; }
;     else if (fo < 8192) { dst = (u16*)(ws + OFF_SGA); ld = 2048; cofs = 6144; act = 2; }
;     else { dst = (u16*)(ws + OFF_SGB); ld = 2048; cofs = 8192; act = 2; }
;     #pragma unroll
;     for (int bj = 0; bj < 2; ++bj)
;       #pragma unroll
;       for (int n = 0; n < 2; ++n) {
;         const int t = EPI_T(bj, n);
;         const float r = rs[t];
;         u16* drow = dst + (size_t)t * ld - cofs;
;         #pragma unroll
;         for (int ai = 0; ai < 2; ++ai)
;           #pragma unroll
;           for (int m = 0; m < 4; ++m) {
;             float v[4];
;             #pragma unroll
;             for (int j = 0; j < 4; ++j) {
;               v[j] = acc[ai][bj][m][n][j] * r;
;               if (act == 2) v[j] = sigm(v[j]);
;             }
;             if (act == 2) {
;               *reinterpret_cast<unsigned*>(reinterpret_cast<unsigned char*>(dst) + (size_t)t * 2048 + (EPI_F(ai, m) - cofs)) =
;                   pk4_u8(v[0], v[1], v[2], v[3]);
.LBB0_167:
	s_or_b64 exec, exec, s[66:67]
	v_and_b32_e32 v130, 15, v194
	v_lshrrev_b32_e32 v131, 1, v194
	v_and_b32_e32 v131, 0x60, v131
	v_add3_u32 v132, s72, v130, v131
	v_lshlrev_b32_e32 v133, 2, v132
	global_load_dword v136, v133, s[30:31]
	global_load_dword v138, v133, s[30:31] offset:64
	global_load_dword v140, v133, s[30:31] offset:512
	global_load_dword v142, v133, s[30:31] offset:576
	v_bfe_u32 v134, v194, 4, 2
	v_lshrrev_b32_e32 v135, 2, v194
	v_and_b32_e32 v135, 0xffffffc0, v135
	s_add_i32 s24, s90, 1
	s_mul_i32 s25, s24, s33
	s_add_i32 s66, s25, s33
	s_mov_b32 s67, s2
	s_and_b32 s76, s33, 7
	s_cmp_lg_u32 s76, 0
	s_cbranch_scc1 .Lp1n_base
	s_cmpk_gt_i32 s66, 0x1900
	s_cbranch_scc1 .Lp1n_base
	s_mov_b32 s67, s35
.Lp1n_base:
	s_add_i32 s24, s67, s25
	s_cmpk_lt_i32 s24, 0x1900
	s_cbranch_scc1 .Lp1n_valid
	s_mov_b32 s100, 0
	s_waitcnt vmcnt(0)
	s_branch .Lp1n_done
.Lp1n_valid:
	s_mul_hi_i32 s25, s24, 0x66666667
	s_lshr_b32 s66, s25, 31
	s_ashr_i32 s25, s25, 7
	s_add_i32 s25, s25, s66
	s_lshl_b32 s66, s25, 3
	s_mulk_i32 s25, 0x140
	s_sub_i32 s24, s24, s25
	s_and_b32 s25, s24, 7
	s_add_i32 s98, s66, s25
	s_lshr_b32 s99, s24, 3
	s_lshl_b32 s98, s98, 8
	s_lshl_b32 s99, s99, 8
	s_lshl_b32 s24, s98, 12
	s_add_u32 s76, s38, s24
	s_addc_u32 s77, s39, 0
	s_or_b32 s24, s98, 0x80
	s_lshl_b32 s24, s24, 12
	s_add_u32 s78, s38, s24
	s_addc_u32 s79, s39, 0
	s_lshl_b32 s24, s99, 12
	s_add_u32 s66, s3, s24
	s_addc_u32 s67, s11, 0
	s_or_b32 s24, s99, 0x80
	s_lshl_b32 s24, s24, 12
	s_add_u32 s24, s3, s24
	s_addc_u32 s25, s11, 0
	s_add_u32 m0, s95, 0x10000
	s_nop 0
	global_load_lds_dwordx4 v250, s[76:77]
	s_add_u32 m0, s95, 0x12000
	s_nop 0
	global_load_lds_dwordx4 v251, s[76:77]
	s_add_u32 m0, s95, 0x0
	s_nop 0
	global_load_lds_dwordx4 v250, s[66:67]
	s_add_u32 m0, s95, 0x2000
	s_nop 0
	global_load_lds_dwordx4 v251, s[66:67]
	s_add_u32 m0, s95, 0x14000
	s_nop 0
	global_load_lds_dwordx4 v250, s[78:79]
	s_add_u32 m0, s95, 0x16000
	s_nop 0
	global_load_lds_dwordx4 v251, s[78:79]
	s_add_u32 m0, s95, 0x4000
	s_nop 0
	global_load_lds_dwordx4 v250, s[24:25]
	s_add_u32 m0, s95, 0x6000
	s_nop 0
	global_load_lds_dwordx4 v251, s[24:25]
	s_mov_b32 s100, 1
.Lp1n_done:
	s_mov_b64 s[66:67], s[42:43]
	s_movk_i32 s70, 0x1000
	s_mov_b32 s7, 0
	s_cmp_lt_i32 s94, 8
	s_cbranch_scc1 .Lp1e_bf16
	s_mov_b64 s[66:67], s[40:41]
	s_movk_i32 s7, 0x800
	s_cmp_lt_u32 s94, 16
	s_cbranch_scc1 .Lp1e_bf16
	s_mov_b64 s[66:67], s[44:45]
	s_movk_i32 s70, 0x800
	s_movk_i32 s7, 0x1000
	s_cmp_lt_u32 s94, 20
	s_cbranch_scc1 .Lp1e_bf16
	s_mov_b64 s[66:67], s[46:47]
	s_movk_i32 s7, 0x1400
	s_cmp_lt_u32 s94, 24
	s_cbranch_scc1 .Lp1e_bf16
	s_add_u32 s66, s30, 0x26000000
	s_addc_u32 s67, s31, 0
	s_movk_i32 s7, 0x1800
	s_cmp_lt_u32 s94, 32
	s_cbranch_scc1 .Lp1e_gate
	s_add_u32 s66, s30, 0x30000000
	s_addc_u32 s67, s31, 0
	s_movk_i32 s7, 0x2000
.Lp1e_gate:
	s_mov_b32 s101, 1
	s_sub_i32 s24, s6, s7
	v_lshl_add_u32 v146, v134, 4, v135
	v_add_u32_e32 v146, s24, v146
	v_lshl_add_u32 v148, v132, 11, v146
	v_add_u32_e32 v149, 0x8000, v148
	v_add_u32_e32 v150, 0x40000, v148
	v_add_u32_e32 v151, 0x48000, v148
	s_waitcnt vmcnt(11)
	v_pk_mul_f32 v[124:125], v[124:125], v[136:137] op_sel_hi:[1,0]
	v_pk_mul_f32 v[126:127], v[126:127], v[136:137] op_sel_hi:[1,0]
	v_mul_f32_e32 v124, 0xbfb8aa3b, v124
	v_mul_f32_e32 v125, 0xbfb8aa3b, v125
	v_mul_f32_e32 v126, 0xbfb8aa3b, v126
	v_mul_f32_e32 v127, 0xbfb8aa3b, v127
	v_exp_f32_e32 v124, v124
	v_exp_f32_e32 v125, v125
	v_exp_f32_e32 v126, v126
	v_exp_f32_e32 v127, v127
	v_add_f32_e32 v124, 1.0, v124
	v_add_f32_e32 v125, 1.0, v125
	v_add_f32_e32 v126, 1.0, v126
	v_add_f32_e32 v127, 1.0, v127
	v_rcp_f32_e64 v124, v124 clamp
	v_rcp_f32_e64 v125, v125 clamp
	v_rcp_f32_e64 v126, v126 clamp
	v_rcp_f32_e64 v127, v127 clamp
	v_mul_f32_e32 v124, 0x437f0000, v124
	v_mul_f32_e32 v125, 0x437f0000, v125
	v_mul_f32_e32 v126, 0x437f0000, v126
	v_mul_f32_e32 v127, 0x437f0000, v127
	v_rndne_f32_e32 v124, v124
	v_rndne_f32_e32 v125, v125
	v_rndne_f32_e32 v126, v126
	v_rndne_f32_e32 v127, v127
	v_cvt_u32_f32_e32 v124, v124
	v_cvt_u32_f32_e32 v125, v125
	v_cvt_u32_f32_sdwa v126, v126 dst_sel:WORD_1 dst_unused:UNUSED_PAD src0_sel:DWORD
	v_cvt_u32_f32_sdwa v127, v127 dst_sel:BYTE_3 dst_unused:UNUSED_PAD src0_sel:DWORD
	v_lshl_or_b32 v160, v125, 8, v124
	v_or3_b32 v160, v160, v126, v127
	v_pk_mul_f32 v[120:121], v[120:121], v[136:137] op_sel_hi:[1,0]
	v_pk_mul_f32 v[122:123], v[122:123], v[136:137] op_sel_hi:[1,0]
	v_mul_f32_e32 v120, 0xbfb8aa3b, v120
	v_mul_f32_e32 v121, 0xbfb8aa3b, v121
	v_mul_f32_e32 v122, 0xbfb8aa3b, v122
	v_mul_f32_e32 v123, 0xbfb8aa3b, v123
	v_exp_f32_e32 v120, v120
	v_exp_f32_e32 v121, v121
	v_exp_f32_e32 v122, v122
	v_exp_f32_e32 v123, v123
	v_add_f32_e32 v120, 1.0, v120
	v_add_f32_e32 v121, 1.0, v121
	v_add_f32_e32 v122, 1.0, v122
	v_add_f32_e32 v123, 1.0, v123
	v_rcp_f32_e64 v120, v120 clamp
	v_rcp_f32_e64 v121, v121 clamp
	v_rcp_f32_e64 v122, v122 clamp
	v_rcp_f32_e64 v123, v123 clamp
	v_mul_f32_e32 v120, 0x437f0000, v120
	v_mul_f32_e32 v121, 0x437f0000, v121
	v_mul_f32_e32 v122, 0x437f0000, v122
	v_mul_f32_e32 v123, 0x437f0000, v123
	v_rndne_f32_e32 v120, v120
	v_rndne_f32_e32 v121, v121
	v_rndne_f32_e32 v122, v122
	v_rndne_f32_e32 v123, v123
	v_cvt_u32_f32_e32 v120, v120
	v_cvt_u32_f32_e32 v121, v121
	v_cvt_u32_f32_sdwa v122, v122 dst_sel:WORD_1 dst_unused:UNUSED_PAD src0_sel:DWORD
	v_cvt_u32_f32_sdwa v123, v123 dst_sel:BYTE_3 dst_unused:UNUSED_PAD src0_sel:DWORD
	v_lshl_or_b32 v161, v121, 8, v120
	v_or3_b32 v161, v161, v122, v123
	v_pk_mul_f32 v[116:117], v[116:117], v[136:137] op_sel_hi:[1,0]
	v_pk_mul_f32 v[118:119], v[118:119], v[136:137] op_sel_hi:[1,0]
; __device__ void phase1(const Params& p) {
;     ...
;             float v[4];
;             #pragma unroll
;             for (int j = 0; j < 4; ++j) {
;               v[j] = acc[ai][bj][m][n][j] * r;
;               if (act == 2) v[j] = sigm(v[j]);
;             }
;             if (act == 2) {
;               *reinterpret_cast<unsigned*>(reinterpret_cast<unsigned char*>(dst) + (size_t)t * 2048 + (EPI_F(ai, m) - cofs)) =
;                   pk4_u8(v[0], v[1], v[2], v[3]);
	v_mul_f32_e32 v116, 0xbfb8aa3b, v116
	v_mul_f32_e32 v117, 0xbfb8aa3b, v117
	v_mul_f32_e32 v118, 0xbfb8aa3b, v118
	v_mul_f32_e32 v119, 0xbfb8aa3b, v119
	v_exp_f32_e32 v116, v116
	v_exp_f32_e32 v117, v117
	v_exp_f32_e32 v118, v118
	v_exp_f32_e32 v119, v119
	v_add_f32_e32 v116, 1.0, v116
	v_add_f32_e32 v117, 1.0, v117
	v_add_f32_e32 v118, 1.0, v118
	v_add_f32_e32 v119, 1.0, v119
	v_rcp_f32_e64 v116, v116 clamp
	v_rcp_f32_e64 v117, v117 clamp
	v_rcp_f32_e64 v118, v118 clamp
	v_rcp_f32_e64 v119, v119 clamp
	v_mul_f32_e32 v116, 0x437f0000, v116
	v_mul_f32_e32 v117, 0x437f0000, v117
	v_mul_f32_e32 v118, 0x437f0000, v118
	v_mul_f32_e32 v119, 0x437f0000, v119
	v_rndne_f32_e32 v116, v116
	v_rndne_f32_e32 v117, v117
	v_rndne_f32_e32 v118, v118
	v_rndne_f32_e32 v119, v119
	v_cvt_u32_f32_e32 v116, v116
	v_cvt_u32_f32_e32 v117, v117
	v_cvt_u32_f32_sdwa v118, v118 dst_sel:WORD_1 dst_unused:UNUSED_PAD src0_sel:DWORD
	v_cvt_u32_f32_sdwa v119, v119 dst_sel:BYTE_3 dst_unused:UNUSED_PAD src0_sel:DWORD
	v_lshl_or_b32 v162, v117, 8, v116
	v_or3_b32 v162, v162, v118, v119
	v_pk_mul_f32 v[112:113], v[112:113], v[136:137] op_sel_hi:[1,0]
	v_pk_mul_f32 v[114:115], v[114:115], v[136:137] op_sel_hi:[1,0]
	v_mul_f32_e32 v112, 0xbfb8aa3b, v112
	v_mul_f32_e32 v113, 0xbfb8aa3b, v113
	v_mul_f32_e32 v114, 0xbfb8aa3b, v114
	v_mul_f32_e32 v115, 0xbfb8aa3b, v115
	v_exp_f32_e32 v112, v112
	v_exp_f32_e32 v113, v113
	v_exp_f32_e32 v114, v114
	v_exp_f32_e32 v115, v115
	v_add_f32_e32 v112, 1.0, v112
	v_add_f32_e32 v113, 1.0, v113
	v_add_f32_e32 v114, 1.0, v114
	v_add_f32_e32 v115, 1.0, v115
	v_rcp_f32_e64 v112, v112 clamp
	v_rcp_f32_e64 v113, v113 clamp
	v_rcp_f32_e64 v114, v114 clamp
	v_rcp_f32_e64 v115, v115 clamp
	v_mul_f32_e32 v112, 0x437f0000, v112
	v_mul_f32_e32 v113, 0x437f0000, v113
	v_mul_f32_e32 v114, 0x437f0000, v114
	v_mul_f32_e32 v115, 0x437f0000, v115
	v_rndne_f32_e32 v112, v112
	v_rndne_f32_e32 v113, v113
	v_rndne_f32_e32 v114, v114
	v_rndne_f32_e32 v115, v115
	v_cvt_u32_f32_e32 v112, v112
	v_cvt_u32_f32_e32 v113, v113
	v_cvt_u32_f32_sdwa v114, v114 dst_sel:WORD_1 dst_unused:UNUSED_PAD src0_sel:DWORD
	v_cvt_u32_f32_sdwa v115, v115 dst_sel:BYTE_3 dst_unused:UNUSED_PAD src0_sel:DWORD
	v_lshl_or_b32 v163, v113, 8, v112
	v_or3_b32 v163, v163, v114, v115
	s_nop 1
	v_permlane16_swap_b32 v160, v161
	v_permlane16_swap_b32 v162, v163
	s_nop 1
	v_permlane32_swap_b32 v160, v162
	v_permlane32_swap_b32 v161, v163
	global_store_dwordx4 v148, v[160:163], s[66:67]
	v_pk_mul_f32 v[108:109], v[108:109], v[136:137] op_sel_hi:[1,0]
	v_pk_mul_f32 v[110:111], v[110:111], v[136:137] op_sel_hi:[1,0]
	v_mul_f32_e32 v108, 0xbfb8aa3b, v108
	v_mul_f32_e32 v109, 0xbfb8aa3b, v109
	v_mul_f32_e32 v110, 0xbfb8aa3b, v110
	v_mul_f32_e32 v111, 0xbfb8aa3b, v111
	v_exp_f32_e32 v108, v108
	v_exp_f32_e32 v109, v109
	v_exp_f32_e32 v110, v110
	v_exp_f32_e32 v111, v111
	v_add_f32_e32 v108, 1.0, v108
	v_add_f32_e32 v109, 1.0, v109
	v_add_f32_e32 v110, 1.0, v110
	v_add_f32_e32 v111, 1.0, v111
	v_rcp_f32_e64 v108, v108 clamp
	v_rcp_f32_e64 v109, v109 clamp
	v_rcp_f32_e64 v110, v110 clamp
	v_rcp_f32_e64 v111, v111 clamp
	v_mul_f32_e32 v108, 0x437f0000, v108
	v_mul_f32_e32 v109, 0x437f0000, v109
	v_mul_f32_e32 v110, 0x437f0000, v110
	v_mul_f32_e32 v111, 0x437f0000, v111
	v_rndne_f32_e32 v108, v108
	v_rndne_f32_e32 v109, v109
	v_rndne_f32_e32 v110, v110
	v_rndne_f32_e32 v111, v111
	v_cvt_u32_f32_e32 v108, v108
	v_cvt_u32_f32_e32 v109, v109
	v_cvt_u32_f32_sdwa v110, v110 dst_sel:WORD_1 dst_unused:UNUSED_PAD src0_sel:DWORD
	v_cvt_u32_f32_sdwa v111, v111 dst_sel:BYTE_3 dst_unused:UNUSED_PAD src0_sel:DWORD
	v_lshl_or_b32 v164, v109, 8, v108
	v_or3_b32 v164, v164, v110, v111
	v_pk_mul_f32 v[104:105], v[104:105], v[136:137] op_sel_hi:[1,0]
	v_pk_mul_f32 v[106:107], v[106:107], v[136:137] op_sel_hi:[1,0]
	v_mul_f32_e32 v104, 0xbfb8aa3b, v104
	v_mul_f32_e32 v105, 0xbfb8aa3b, v105
	v_mul_f32_e32 v106, 0xbfb8aa3b, v106
	v_mul_f32_e32 v107, 0xbfb8aa3b, v107
	v_exp_f32_e32 v104, v104
	v_exp_f32_e32 v105, v105
	v_exp_f32_e32 v106, v106
	v_exp_f32_e32 v107, v107
	v_add_f32_e32 v104, 1.0, v104
	v_add_f32_e32 v105, 1.0, v105
	v_add_f32_e32 v106, 1.0, v106
	v_add_f32_e32 v107, 1.0, v107
	v_rcp_f32_e64 v104, v104 clamp
	v_rcp_f32_e64 v105, v105 clamp
	v_rcp_f32_e64 v106, v106 clamp
	v_rcp_f32_e64 v107, v107 clamp
	v_mul_f32_e32 v104, 0x437f0000, v104
	v_mul_f32_e32 v105, 0x437f0000, v105
	v_mul_f32_e32 v106, 0x437f0000, v106
	v_mul_f32_e32 v107, 0x437f0000, v107
	v_rndne_f32_e32 v104, v104
	v_rndne_f32_e32 v105, v105
	v_rndne_f32_e32 v106, v106
	v_rndne_f32_e32 v107, v107
	v_cvt_u32_f32_e32 v104, v104
	v_cvt_u32_f32_e32 v105, v105
	v_cvt_u32_f32_sdwa v106, v106 dst_sel:WORD_1 dst_unused:UNUSED_PAD src0_sel:DWORD
	v_cvt_u32_f32_sdwa v107, v107 dst_sel:BYTE_3 dst_unused:UNUSED_PAD src0_sel:DWORD
	v_lshl_or_b32 v165, v105, 8, v104
	v_or3_b32 v165, v165, v106, v107
	v_pk_mul_f32 v[100:101], v[100:101], v[136:137] op_sel_hi:[1,0]
	v_pk_mul_f32 v[102:103], v[102:103], v[136:137] op_sel_hi:[1,0]
	v_mul_f32_e32 v100, 0xbfb8aa3b, v100
	v_mul_f32_e32 v101, 0xbfb8aa3b, v101
	v_mul_f32_e32 v102, 0xbfb8aa3b, v102
	v_mul_f32_e32 v103, 0xbfb8aa3b, v103
	v_exp_f32_e32 v100, v100
	v_exp_f32_e32 v101, v101
	v_exp_f32_e32 v102, v102
	v_exp_f32_e32 v103, v103
	v_add_f32_e32 v100, 1.0, v100
	v_add_f32_e32 v101, 1.0, v101
	v_add_f32_e32 v102, 1.0, v102
	v_add_f32_e32 v103, 1.0, v103
	v_rcp_f32_e64 v100, v100 clamp
	v_rcp_f32_e64 v101, v101 clamp
	v_rcp_f32_e64 v102, v102 clamp
	v_rcp_f32_e64 v103, v103 clamp
	v_mul_f32_e32 v100, 0x437f0000, v100
	v_mul_f32_e32 v101, 0x437f0000, v101
	v_mul_f32_e32 v102, 0x437f0000, v102
	v_mul_f32_e32 v103, 0x437f0000, v103
; __device__ void phase1(const Params& p) {
;     ...
;         const int t = EPI_T(bj, n);
;         const float r = rs[t];
;         u16* drow = dst + (size_t)t * ld - cofs;
;         #pragma unroll
;         for (int ai = 0; ai < 2; ++ai)
;           #pragma unroll
;           for (int m = 0; m < 4; ++m) {
;             float v[4];
;             #pragma unroll
;             for (int j = 0; j < 4; ++j) {
;               v[j] = acc[ai][bj][m][n][j] * r;
;               if (act == 2) v[j] = sigm(v[j]);
;             }
;             if (act == 2) {
;               *reinterpret_cast<unsigned*>(reinterpret_cast<unsigned char*>(dst) + (size_t)t * 2048 + (EPI_F(ai, m) - cofs)) =
;                   pk4_u8(v[0], v[1], v[2], v[3]);
	v_rndne_f32_e32 v100, v100
	v_rndne_f32_e32 v101, v101
	v_rndne_f32_e32 v102, v102
	v_rndne_f32_e32 v103, v103
	v_cvt_u32_f32_e32 v100, v100
	v_cvt_u32_f32_e32 v101, v101
	v_cvt_u32_f32_sdwa v102, v102 dst_sel:WORD_1 dst_unused:UNUSED_PAD src0_sel:DWORD
	v_cvt_u32_f32_sdwa v103, v103 dst_sel:BYTE_3 dst_unused:UNUSED_PAD src0_sel:DWORD
	v_lshl_or_b32 v166, v101, 8, v100
	v_or3_b32 v166, v166, v102, v103
	v_pk_mul_f32 v[96:97], v[96:97], v[136:137] op_sel_hi:[1,0]
	v_pk_mul_f32 v[98:99], v[98:99], v[136:137] op_sel_hi:[1,0]
	v_mul_f32_e32 v96, 0xbfb8aa3b, v96
	v_mul_f32_e32 v97, 0xbfb8aa3b, v97
	v_mul_f32_e32 v98, 0xbfb8aa3b, v98
	v_mul_f32_e32 v99, 0xbfb8aa3b, v99
	v_exp_f32_e32 v96, v96
	v_exp_f32_e32 v97, v97
	v_exp_f32_e32 v98, v98
	v_exp_f32_e32 v99, v99
	v_add_f32_e32 v96, 1.0, v96
	v_add_f32_e32 v97, 1.0, v97
	v_add_f32_e32 v98, 1.0, v98
	v_add_f32_e32 v99, 1.0, v99
	v_rcp_f32_e64 v96, v96 clamp
	v_rcp_f32_e64 v97, v97 clamp
	v_rcp_f32_e64 v98, v98 clamp
	v_rcp_f32_e64 v99, v99 clamp
	v_mul_f32_e32 v96, 0x437f0000, v96
	v_mul_f32_e32 v97, 0x437f0000, v97
	v_mul_f32_e32 v98, 0x437f0000, v98
	v_mul_f32_e32 v99, 0x437f0000, v99
	v_rndne_f32_e32 v96, v96
	v_rndne_f32_e32 v97, v97
	v_rndne_f32_e32 v98, v98
	v_rndne_f32_e32 v99, v99
	v_cvt_u32_f32_e32 v96, v96
	v_cvt_u32_f32_e32 v97, v97
	v_cvt_u32_f32_sdwa v98, v98 dst_sel:WORD_1 dst_unused:UNUSED_PAD src0_sel:DWORD
	v_cvt_u32_f32_sdwa v99, v99 dst_sel:BYTE_3 dst_unused:UNUSED_PAD src0_sel:DWORD
	v_lshl_or_b32 v167, v97, 8, v96
	v_or3_b32 v167, v167, v98, v99
	s_nop 1
	v_permlane16_swap_b32 v164, v165
	v_permlane16_swap_b32 v166, v167
	s_nop 1
	v_permlane32_swap_b32 v164, v166
	v_permlane32_swap_b32 v165, v167
	global_store_dwordx4 v148, v[164:167], s[66:67] offset:128
	s_waitcnt vmcnt(12)
	v_pk_mul_f32 v[92:93], v[92:93], v[138:139] op_sel_hi:[1,0]
	v_pk_mul_f32 v[94:95], v[94:95], v[138:139] op_sel_hi:[1,0]
	v_mul_f32_e32 v92, 0xbfb8aa3b, v92
	v_mul_f32_e32 v93, 0xbfb8aa3b, v93
	v_mul_f32_e32 v94, 0xbfb8aa3b, v94
	v_mul_f32_e32 v95, 0xbfb8aa3b, v95
	v_exp_f32_e32 v92, v92
	v_exp_f32_e32 v93, v93
	v_exp_f32_e32 v94, v94
	v_exp_f32_e32 v95, v95
	v_add_f32_e32 v92, 1.0, v92
	v_add_f32_e32 v93, 1.0, v93
	v_add_f32_e32 v94, 1.0, v94
	v_add_f32_e32 v95, 1.0, v95
	v_rcp_f32_e64 v92, v92 clamp
	v_rcp_f32_e64 v93, v93 clamp
	v_rcp_f32_e64 v94, v94 clamp
	v_rcp_f32_e64 v95, v95 clamp
	v_mul_f32_e32 v92, 0x437f0000, v92
	v_mul_f32_e32 v93, 0x437f0000, v93
	v_mul_f32_e32 v94, 0x437f0000, v94
	v_mul_f32_e32 v95, 0x437f0000, v95
	v_rndne_f32_e32 v92, v92
	v_rndne_f32_e32 v93, v93
	v_rndne_f32_e32 v94, v94
	v_rndne_f32_e32 v95, v95
	v_cvt_u32_f32_e32 v92, v92
	v_cvt_u32_f32_e32 v93, v93
	v_cvt_u32_f32_sdwa v94, v94 dst_sel:WORD_1 dst_unused:UNUSED_PAD src0_sel:DWORD
	v_cvt_u32_f32_sdwa v95, v95 dst_sel:BYTE_3 dst_unused:UNUSED_PAD src0_sel:DWORD
	v_lshl_or_b32 v168, v93, 8, v92
	v_or3_b32 v168, v168, v94, v95
	v_pk_mul_f32 v[88:89], v[88:89], v[138:139] op_sel_hi:[1,0]
	v_pk_mul_f32 v[90:91], v[90:91], v[138:139] op_sel_hi:[1,0]
	v_mul_f32_e32 v88, 0xbfb8aa3b, v88
	v_mul_f32_e32 v89, 0xbfb8aa3b, v89
	v_mul_f32_e32 v90, 0xbfb8aa3b, v90
	v_mul_f32_e32 v91, 0xbfb8aa3b, v91
	v_exp_f32_e32 v88, v88
	v_exp_f32_e32 v89, v89
	v_exp_f32_e32 v90, v90
	v_exp_f32_e32 v91, v91
	v_add_f32_e32 v88, 1.0, v88
	v_add_f32_e32 v89, 1.0, v89
	v_add_f32_e32 v90, 1.0, v90
	v_add_f32_e32 v91, 1.0, v91
	v_rcp_f32_e64 v88, v88 clamp
	v_rcp_f32_e64 v89, v89 clamp
	v_rcp_f32_e64 v90, v90 clamp
	v_rcp_f32_e64 v91, v91 clamp
	v_mul_f32_e32 v88, 0x437f0000, v88
	v_mul_f32_e32 v89, 0x437f0000, v89
	v_mul_f32_e32 v90, 0x437f0000, v90
	v_mul_f32_e32 v91, 0x437f0000, v91
	v_rndne_f32_e32 v88, v88
	v_rndne_f32_e32 v89, v89
	v_rndne_f32_e32 v90, v90
	v_rndne_f32_e32 v91, v91
	v_cvt_u32_f32_e32 v88, v88
	v_cvt_u32_f32_e32 v89, v89
	v_cvt_u32_f32_sdwa v90, v90 dst_sel:WORD_1 dst_unused:UNUSED_PAD src0_sel:DWORD
	v_cvt_u32_f32_sdwa v91, v91 dst_sel:BYTE_3 dst_unused:UNUSED_PAD src0_sel:DWORD
	v_lshl_or_b32 v169, v89, 8, v88
	v_or3_b32 v169, v169, v90, v91
	v_pk_mul_f32 v[84:85], v[84:85], v[138:139] op_sel_hi:[1,0]
	v_pk_mul_f32 v[86:87], v[86:87], v[138:139] op_sel_hi:[1,0]
	v_mul_f32_e32 v84, 0xbfb8aa3b, v84
	v_mul_f32_e32 v85, 0xbfb8aa3b, v85
	v_mul_f32_e32 v86, 0xbfb8aa3b, v86
	v_mul_f32_e32 v87, 0xbfb8aa3b, v87
	v_exp_f32_e32 v84, v84
	v_exp_f32_e32 v85, v85
	v_exp_f32_e32 v86, v86
	v_exp_f32_e32 v87, v87
	v_add_f32_e32 v84, 1.0, v84
	v_add_f32_e32 v85, 1.0, v85
	v_add_f32_e32 v86, 1.0, v86
	v_add_f32_e32 v87, 1.0, v87
	v_rcp_f32_e64 v84, v84 clamp
	v_rcp_f32_e64 v85, v85 clamp
	v_rcp_f32_e64 v86, v86 clamp
	v_rcp_f32_e64 v87, v87 clamp
	v_mul_f32_e32 v84, 0x437f0000, v84
	v_mul_f32_e32 v85, 0x437f0000, v85
	v_mul_f32_e32 v86, 0x437f0000, v86
	v_mul_f32_e32 v87, 0x437f0000, v87
	v_rndne_f32_e32 v84, v84
	v_rndne_f32_e32 v85, v85
	v_rndne_f32_e32 v86, v86
	v_rndne_f32_e32 v87, v87
	v_cvt_u32_f32_e32 v84, v84
	v_cvt_u32_f32_e32 v85, v85
	v_cvt_u32_f32_sdwa v86, v86 dst_sel:WORD_1 dst_unused:UNUSED_PAD src0_sel:DWORD
	v_cvt_u32_f32_sdwa v87, v87 dst_sel:BYTE_3 dst_unused:UNUSED_PAD src0_sel:DWORD
	v_lshl_or_b32 v170, v85, 8, v84
	v_or3_b32 v170, v170, v86, v87
	v_pk_mul_f32 v[80:81], v[80:81], v[138:139] op_sel_hi:[1,0]
	v_pk_mul_f32 v[82:83], v[82:83], v[138:139] op_sel_hi:[1,0]
	v_mul_f32_e32 v80, 0xbfb8aa3b, v80
	v_mul_f32_e32 v81, 0xbfb8aa3b, v81
	v_mul_f32_e32 v82, 0xbfb8aa3b, v82
	v_mul_f32_e32 v83, 0xbfb8aa3b, v83
	v_exp_f32_e32 v80, v80
	v_exp_f32_e32 v81, v81
	v_exp_f32_e32 v82, v82
	v_exp_f32_e32 v83, v83
	v_add_f32_e32 v80, 1.0, v80
	v_add_f32_e32 v81, 1.0, v81
	v_add_f32_e32 v82, 1.0, v82
	v_add_f32_e32 v83, 1.0, v83
; __device__ void phase1(const Params& p) {
;     ...
;         const int t = EPI_T(bj, n);
;         const float r = rs[t];
;         u16* drow = dst + (size_t)t * ld - cofs;
;         #pragma unroll
;         for (int ai = 0; ai < 2; ++ai)
;           #pragma unroll
;           for (int m = 0; m < 4; ++m) {
;             float v[4];
;             #pragma unroll
;             for (int j = 0; j < 4; ++j) {
;               v[j] = acc[ai][bj][m][n][j] * r;
;               if (act == 2) v[j] = sigm(v[j]);
;             }
;             if (act == 2) {
;               *reinterpret_cast<unsigned*>(reinterpret_cast<unsigned char*>(dst) + (size_t)t * 2048 + (EPI_F(ai, m) - cofs)) =
;                   pk4_u8(v[0], v[1], v[2], v[3]);
	v_rcp_f32_e64 v80, v80 clamp
	v_rcp_f32_e64 v81, v81 clamp
	v_rcp_f32_e64 v82, v82 clamp
	v_rcp_f32_e64 v83, v83 clamp
	v_mul_f32_e32 v80, 0x437f0000, v80
	v_mul_f32_e32 v81, 0x437f0000, v81
	v_mul_f32_e32 v82, 0x437f0000, v82
	v_mul_f32_e32 v83, 0x437f0000, v83
	v_rndne_f32_e32 v80, v80
	v_rndne_f32_e32 v81, v81
	v_rndne_f32_e32 v82, v82
	v_rndne_f32_e32 v83, v83
	v_cvt_u32_f32_e32 v80, v80
	v_cvt_u32_f32_e32 v81, v81
	v_cvt_u32_f32_sdwa v82, v82 dst_sel:WORD_1 dst_unused:UNUSED_PAD src0_sel:DWORD
	v_cvt_u32_f32_sdwa v83, v83 dst_sel:BYTE_3 dst_unused:UNUSED_PAD src0_sel:DWORD
	v_lshl_or_b32 v171, v81, 8, v80
	v_or3_b32 v171, v171, v82, v83
	s_nop 1
	v_permlane16_swap_b32 v168, v169
	v_permlane16_swap_b32 v170, v171
	s_nop 1
	v_permlane32_swap_b32 v168, v170
	v_permlane32_swap_b32 v169, v171
	global_store_dwordx4 v149, v[168:171], s[66:67]
	v_pk_mul_f32 v[76:77], v[76:77], v[138:139] op_sel_hi:[1,0]
	v_pk_mul_f32 v[78:79], v[78:79], v[138:139] op_sel_hi:[1,0]
	v_mul_f32_e32 v76, 0xbfb8aa3b, v76
	v_mul_f32_e32 v77, 0xbfb8aa3b, v77
	v_mul_f32_e32 v78, 0xbfb8aa3b, v78
	v_mul_f32_e32 v79, 0xbfb8aa3b, v79
	v_exp_f32_e32 v76, v76
	v_exp_f32_e32 v77, v77
	v_exp_f32_e32 v78, v78
	v_exp_f32_e32 v79, v79
	v_add_f32_e32 v76, 1.0, v76
	v_add_f32_e32 v77, 1.0, v77
	v_add_f32_e32 v78, 1.0, v78
	v_add_f32_e32 v79, 1.0, v79
	v_rcp_f32_e64 v76, v76 clamp
	v_rcp_f32_e64 v77, v77 clamp
	v_rcp_f32_e64 v78, v78 clamp
	v_rcp_f32_e64 v79, v79 clamp
	v_mul_f32_e32 v76, 0x437f0000, v76
	v_mul_f32_e32 v77, 0x437f0000, v77
	v_mul_f32_e32 v78, 0x437f0000, v78
	v_mul_f32_e32 v79, 0x437f0000, v79
	v_rndne_f32_e32 v76, v76
	v_rndne_f32_e32 v77, v77
	v_rndne_f32_e32 v78, v78
	v_rndne_f32_e32 v79, v79
	v_cvt_u32_f32_e32 v76, v76
	v_cvt_u32_f32_e32 v77, v77
	v_cvt_u32_f32_sdwa v78, v78 dst_sel:WORD_1 dst_unused:UNUSED_PAD src0_sel:DWORD
	v_cvt_u32_f32_sdwa v79, v79 dst_sel:BYTE_3 dst_unused:UNUSED_PAD src0_sel:DWORD
	v_lshl_or_b32 v172, v77, 8, v76
	v_or3_b32 v172, v172, v78, v79
	v_pk_mul_f32 v[72:73], v[72:73], v[138:139] op_sel_hi:[1,0]
	v_pk_mul_f32 v[74:75], v[74:75], v[138:139] op_sel_hi:[1,0]
	v_mul_f32_e32 v72, 0xbfb8aa3b, v72
	v_mul_f32_e32 v73, 0xbfb8aa3b, v73
	v_mul_f32_e32 v74, 0xbfb8aa3b, v74
	v_mul_f32_e32 v75, 0xbfb8aa3b, v75
	v_exp_f32_e32 v72, v72
	v_exp_f32_e32 v73, v73
	v_exp_f32_e32 v74, v74
	v_exp_f32_e32 v75, v75
	v_add_f32_e32 v72, 1.0, v72
	v_add_f32_e32 v73, 1.0, v73
	v_add_f32_e32 v74, 1.0, v74
	v_add_f32_e32 v75, 1.0, v75
	v_rcp_f32_e64 v72, v72 clamp
	v_rcp_f32_e64 v73, v73 clamp
	v_rcp_f32_e64 v74, v74 clamp
	v_rcp_f32_e64 v75, v75 clamp
	v_mul_f32_e32 v72, 0x437f0000, v72
	v_mul_f32_e32 v73, 0x437f0000, v73
	v_mul_f32_e32 v74, 0x437f0000, v74
	v_mul_f32_e32 v75, 0x437f0000, v75
	v_rndne_f32_e32 v72, v72
	v_rndne_f32_e32 v73, v73
	v_rndne_f32_e32 v74, v74
	v_rndne_f32_e32 v75, v75
	v_cvt_u32_f32_e32 v72, v72
	v_cvt_u32_f32_e32 v73, v73
	v_cvt_u32_f32_sdwa v74, v74 dst_sel:WORD_1 dst_unused:UNUSED_PAD src0_sel:DWORD
	v_cvt_u32_f32_sdwa v75, v75 dst_sel:BYTE_3 dst_unused:UNUSED_PAD src0_sel:DWORD
	v_lshl_or_b32 v173, v73, 8, v72
	v_or3_b32 v173, v173, v74, v75
	v_pk_mul_f32 v[68:69], v[68:69], v[138:139] op_sel_hi:[1,0]
	v_pk_mul_f32 v[70:71], v[70:71], v[138:139] op_sel_hi:[1,0]
	v_mul_f32_e32 v68, 0xbfb8aa3b, v68
	v_mul_f32_e32 v69, 0xbfb8aa3b, v69
	v_mul_f32_e32 v70, 0xbfb8aa3b, v70
	v_mul_f32_e32 v71, 0xbfb8aa3b, v71
	v_exp_f32_e32 v68, v68
	v_exp_f32_e32 v69, v69
	v_exp_f32_e32 v70, v70
	v_exp_f32_e32 v71, v71
	v_add_f32_e32 v68, 1.0, v68
	v_add_f32_e32 v69, 1.0, v69
	v_add_f32_e32 v70, 1.0, v70
	v_add_f32_e32 v71, 1.0, v71
	v_rcp_f32_e64 v68, v68 clamp
	v_rcp_f32_e64 v69, v69 clamp
	v_rcp_f32_e64 v70, v70 clamp
	v_rcp_f32_e64 v71, v71 clamp
	v_mul_f32_e32 v68, 0x437f0000, v68
	v_mul_f32_e32 v69, 0x437f0000, v69
	v_mul_f32_e32 v70, 0x437f0000, v70
	v_mul_f32_e32 v71, 0x437f0000, v71
	v_rndne_f32_e32 v68, v68
	v_rndne_f32_e32 v69, v69
	v_rndne_f32_e32 v70, v70
	v_rndne_f32_e32 v71, v71
	v_cvt_u32_f32_e32 v68, v68
	v_cvt_u32_f32_e32 v69, v69
	v_cvt_u32_f32_sdwa v70, v70 dst_sel:WORD_1 dst_unused:UNUSED_PAD src0_sel:DWORD
	v_cvt_u32_f32_sdwa v71, v71 dst_sel:BYTE_3 dst_unused:UNUSED_PAD src0_sel:DWORD
	v_lshl_or_b32 v174, v69, 8, v68
	v_or3_b32 v174, v174, v70, v71
	v_pk_mul_f32 v[64:65], v[64:65], v[138:139] op_sel_hi:[1,0]
	v_pk_mul_f32 v[66:67], v[66:67], v[138:139] op_sel_hi:[1,0]
	v_mul_f32_e32 v64, 0xbfb8aa3b, v64
	v_mul_f32_e32 v65, 0xbfb8aa3b, v65
	v_mul_f32_e32 v66, 0xbfb8aa3b, v66
	v_mul_f32_e32 v67, 0xbfb8aa3b, v67
	v_exp_f32_e32 v64, v64
	v_exp_f32_e32 v65, v65
	v_exp_f32_e32 v66, v66
	v_exp_f32_e32 v67, v67
	v_add_f32_e32 v64, 1.0, v64
	v_add_f32_e32 v65, 1.0, v65
	v_add_f32_e32 v66, 1.0, v66
	v_add_f32_e32 v67, 1.0, v67
	v_rcp_f32_e64 v64, v64 clamp
	v_rcp_f32_e64 v65, v65 clamp
	v_rcp_f32_e64 v66, v66 clamp
	v_rcp_f32_e64 v67, v67 clamp
	v_mul_f32_e32 v64, 0x437f0000, v64
	v_mul_f32_e32 v65, 0x437f0000, v65
	v_mul_f32_e32 v66, 0x437f0000, v66
	v_mul_f32_e32 v67, 0x437f0000, v67
	v_rndne_f32_e32 v64, v64
	v_rndne_f32_e32 v65, v65
	v_rndne_f32_e32 v66, v66
	v_rndne_f32_e32 v67, v67
	v_cvt_u32_f32_e32 v64, v64
	v_cvt_u32_f32_e32 v65, v65
	v_cvt_u32_f32_sdwa v66, v66 dst_sel:WORD_1 dst_unused:UNUSED_PAD src0_sel:DWORD
	v_cvt_u32_f32_sdwa v67, v67 dst_sel:BYTE_3 dst_unused:UNUSED_PAD src0_sel:DWORD
	v_lshl_or_b32 v175, v65, 8, v64
	v_or3_b32 v175, v175, v66, v67
	s_nop 1
	v_permlane16_swap_b32 v172, v173
	v_permlane16_swap_b32 v174, v175
	s_nop 1
	v_permlane32_swap_b32 v172, v174
	v_permlane32_swap_b32 v173, v175
	global_store_dwordx4 v149, v[172:175], s[66:67] offset:128
	s_waitcnt vmcnt(13)
; __device__ void phase1(const Params& p) {
;     ...
;         const int t = EPI_T(bj, n);
;         const float r = rs[t];
;         u16* drow = dst + (size_t)t * ld - cofs;
;         #pragma unroll
;         for (int ai = 0; ai < 2; ++ai)
;           #pragma unroll
;           for (int m = 0; m < 4; ++m) {
;             float v[4];
;             #pragma unroll
;             for (int j = 0; j < 4; ++j) {
;               v[j] = acc[ai][bj][m][n][j] * r;
;               if (act == 2) v[j] = sigm(v[j]);
;             }
;             if (act == 2) {
;               *reinterpret_cast<unsigned*>(reinterpret_cast<unsigned char*>(dst) + (size_t)t * 2048 + (EPI_F(ai, m) - cofs)) =
;                   pk4_u8(v[0], v[1], v[2], v[3]);
	v_pk_mul_f32 v[60:61], v[60:61], v[140:141] op_sel_hi:[1,0]
	v_pk_mul_f32 v[62:63], v[62:63], v[140:141] op_sel_hi:[1,0]
	v_mul_f32_e32 v60, 0xbfb8aa3b, v60
	v_mul_f32_e32 v61, 0xbfb8aa3b, v61
	v_mul_f32_e32 v62, 0xbfb8aa3b, v62
	v_mul_f32_e32 v63, 0xbfb8aa3b, v63
	v_exp_f32_e32 v60, v60
	v_exp_f32_e32 v61, v61
	v_exp_f32_e32 v62, v62
	v_exp_f32_e32 v63, v63
	v_add_f32_e32 v60, 1.0, v60
	v_add_f32_e32 v61, 1.0, v61
	v_add_f32_e32 v62, 1.0, v62
	v_add_f32_e32 v63, 1.0, v63
	v_rcp_f32_e64 v60, v60 clamp
	v_rcp_f32_e64 v61, v61 clamp
	v_rcp_f32_e64 v62, v62 clamp
	v_rcp_f32_e64 v63, v63 clamp
	v_mul_f32_e32 v60, 0x437f0000, v60
	v_mul_f32_e32 v61, 0x437f0000, v61
	v_mul_f32_e32 v62, 0x437f0000, v62
	v_mul_f32_e32 v63, 0x437f0000, v63
	v_rndne_f32_e32 v60, v60
	v_rndne_f32_e32 v61, v61
	v_rndne_f32_e32 v62, v62
	v_rndne_f32_e32 v63, v63
	v_cvt_u32_f32_e32 v60, v60
	v_cvt_u32_f32_e32 v61, v61
	v_cvt_u32_f32_sdwa v62, v62 dst_sel:WORD_1 dst_unused:UNUSED_PAD src0_sel:DWORD
	v_cvt_u32_f32_sdwa v63, v63 dst_sel:BYTE_3 dst_unused:UNUSED_PAD src0_sel:DWORD
	v_lshl_or_b32 v176, v61, 8, v60
	v_or3_b32 v176, v176, v62, v63
	v_pk_mul_f32 v[56:57], v[56:57], v[140:141] op_sel_hi:[1,0]
	v_pk_mul_f32 v[58:59], v[58:59], v[140:141] op_sel_hi:[1,0]
	v_mul_f32_e32 v56, 0xbfb8aa3b, v56
	v_mul_f32_e32 v57, 0xbfb8aa3b, v57
	v_mul_f32_e32 v58, 0xbfb8aa3b, v58
	v_mul_f32_e32 v59, 0xbfb8aa3b, v59
	v_exp_f32_e32 v56, v56
	v_exp_f32_e32 v57, v57
	v_exp_f32_e32 v58, v58
	v_exp_f32_e32 v59, v59
	v_add_f32_e32 v56, 1.0, v56
	v_add_f32_e32 v57, 1.0, v57
	v_add_f32_e32 v58, 1.0, v58
	v_add_f32_e32 v59, 1.0, v59
	v_rcp_f32_e64 v56, v56 clamp
	v_rcp_f32_e64 v57, v57 clamp
	v_rcp_f32_e64 v58, v58 clamp
	v_rcp_f32_e64 v59, v59 clamp
	v_mul_f32_e32 v56, 0x437f0000, v56
	v_mul_f32_e32 v57, 0x437f0000, v57
	v_mul_f32_e32 v58, 0x437f0000, v58
	v_mul_f32_e32 v59, 0x437f0000, v59
	v_rndne_f32_e32 v56, v56
	v_rndne_f32_e32 v57, v57
	v_rndne_f32_e32 v58, v58
	v_rndne_f32_e32 v59, v59
	v_cvt_u32_f32_e32 v56, v56
	v_cvt_u32_f32_e32 v57, v57
	v_cvt_u32_f32_sdwa v58, v58 dst_sel:WORD_1 dst_unused:UNUSED_PAD src0_sel:DWORD
	v_cvt_u32_f32_sdwa v59, v59 dst_sel:BYTE_3 dst_unused:UNUSED_PAD src0_sel:DWORD
	v_lshl_or_b32 v177, v57, 8, v56
	v_or3_b32 v177, v177, v58, v59
	v_pk_mul_f32 v[52:53], v[52:53], v[140:141] op_sel_hi:[1,0]
	v_pk_mul_f32 v[54:55], v[54:55], v[140:141] op_sel_hi:[1,0]
	v_mul_f32_e32 v52, 0xbfb8aa3b, v52
	v_mul_f32_e32 v53, 0xbfb8aa3b, v53
	v_mul_f32_e32 v54, 0xbfb8aa3b, v54
	v_mul_f32_e32 v55, 0xbfb8aa3b, v55
	v_exp_f32_e32 v52, v52
	v_exp_f32_e32 v53, v53
	v_exp_f32_e32 v54, v54
	v_exp_f32_e32 v55, v55
	v_add_f32_e32 v52, 1.0, v52
	v_add_f32_e32 v53, 1.0, v53
	v_add_f32_e32 v54, 1.0, v54
	v_add_f32_e32 v55, 1.0, v55
	v_rcp_f32_e64 v52, v52 clamp
	v_rcp_f32_e64 v53, v53 clamp
	v_rcp_f32_e64 v54, v54 clamp
	v_rcp_f32_e64 v55, v55 clamp
	v_mul_f32_e32 v52, 0x437f0000, v52
	v_mul_f32_e32 v53, 0x437f0000, v53
	v_mul_f32_e32 v54, 0x437f0000, v54
	v_mul_f32_e32 v55, 0x437f0000, v55
	v_rndne_f32_e32 v52, v52
	v_rndne_f32_e32 v53, v53
	v_rndne_f32_e32 v54, v54
	v_rndne_f32_e32 v55, v55
	v_cvt_u32_f32_e32 v52, v52
	v_cvt_u32_f32_e32 v53, v53
	v_cvt_u32_f32_sdwa v54, v54 dst_sel:WORD_1 dst_unused:UNUSED_PAD src0_sel:DWORD
	v_cvt_u32_f32_sdwa v55, v55 dst_sel:BYTE_3 dst_unused:UNUSED_PAD src0_sel:DWORD
	v_lshl_or_b32 v178, v53, 8, v52
	v_or3_b32 v178, v178, v54, v55
	v_pk_mul_f32 v[48:49], v[48:49], v[140:141] op_sel_hi:[1,0]
	v_pk_mul_f32 v[50:51], v[50:51], v[140:141] op_sel_hi:[1,0]
	v_mul_f32_e32 v48, 0xbfb8aa3b, v48
	v_mul_f32_e32 v49, 0xbfb8aa3b, v49
	v_mul_f32_e32 v50, 0xbfb8aa3b, v50
	v_mul_f32_e32 v51, 0xbfb8aa3b, v51
	v_exp_f32_e32 v48, v48
	v_exp_f32_e32 v49, v49
	v_exp_f32_e32 v50, v50
	v_exp_f32_e32 v51, v51
	v_add_f32_e32 v48, 1.0, v48
	v_add_f32_e32 v49, 1.0, v49
	v_add_f32_e32 v50, 1.0, v50
	v_add_f32_e32 v51, 1.0, v51
	v_rcp_f32_e64 v48, v48 clamp
	v_rcp_f32_e64 v49, v49 clamp
	v_rcp_f32_e64 v50, v50 clamp
	v_rcp_f32_e64 v51, v51 clamp
	v_mul_f32_e32 v48, 0x437f0000, v48
	v_mul_f32_e32 v49, 0x437f0000, v49
	v_mul_f32_e32 v50, 0x437f0000, v50
	v_mul_f32_e32 v51, 0x437f0000, v51
	v_rndne_f32_e32 v48, v48
	v_rndne_f32_e32 v49, v49
	v_rndne_f32_e32 v50, v50
	v_rndne_f32_e32 v51, v51
	v_cvt_u32_f32_e32 v48, v48
	v_cvt_u32_f32_e32 v49, v49
	v_cvt_u32_f32_sdwa v50, v50 dst_sel:WORD_1 dst_unused:UNUSED_PAD src0_sel:DWORD
	v_cvt_u32_f32_sdwa v51, v51 dst_sel:BYTE_3 dst_unused:UNUSED_PAD src0_sel:DWORD
	v_lshl_or_b32 v179, v49, 8, v48
	v_or3_b32 v179, v179, v50, v51
	s_nop 1
	v_permlane16_swap_b32 v176, v177
	v_permlane16_swap_b32 v178, v179
	s_nop 1
	v_permlane32_swap_b32 v176, v178
	v_permlane32_swap_b32 v177, v179
	global_store_dwordx4 v150, v[176:179], s[66:67]
	v_pk_mul_f32 v[44:45], v[44:45], v[140:141] op_sel_hi:[1,0]
	v_pk_mul_f32 v[46:47], v[46:47], v[140:141] op_sel_hi:[1,0]
	v_mul_f32_e32 v44, 0xbfb8aa3b, v44
	v_mul_f32_e32 v45, 0xbfb8aa3b, v45
	v_mul_f32_e32 v46, 0xbfb8aa3b, v46
	v_mul_f32_e32 v47, 0xbfb8aa3b, v47
	v_exp_f32_e32 v44, v44
	v_exp_f32_e32 v45, v45
	v_exp_f32_e32 v46, v46
	v_exp_f32_e32 v47, v47
	v_add_f32_e32 v44, 1.0, v44
	v_add_f32_e32 v45, 1.0, v45
	v_add_f32_e32 v46, 1.0, v46
	v_add_f32_e32 v47, 1.0, v47
	v_rcp_f32_e64 v44, v44 clamp
	v_rcp_f32_e64 v45, v45 clamp
	v_rcp_f32_e64 v46, v46 clamp
	v_rcp_f32_e64 v47, v47 clamp
	v_mul_f32_e32 v44, 0x437f0000, v44
	v_mul_f32_e32 v45, 0x437f0000, v45
	v_mul_f32_e32 v46, 0x437f0000, v46
	v_mul_f32_e32 v47, 0x437f0000, v47
	v_rndne_f32_e32 v44, v44
	v_rndne_f32_e32 v45, v45
	v_rndne_f32_e32 v46, v46
	v_rndne_f32_e32 v47, v47
	v_cvt_u32_f32_e32 v44, v44
	v_cvt_u32_f32_e32 v45, v45
; __device__ void phase1(const Params& p) {
;     ...
;         const int t = EPI_T(bj, n);
;         const float r = rs[t];
;         u16* drow = dst + (size_t)t * ld - cofs;
;         #pragma unroll
;         for (int ai = 0; ai < 2; ++ai)
;           #pragma unroll
;           for (int m = 0; m < 4; ++m) {
;             float v[4];
;             #pragma unroll
;             for (int j = 0; j < 4; ++j) {
;               v[j] = acc[ai][bj][m][n][j] * r;
;               if (act == 2) v[j] = sigm(v[j]);
;             }
;             if (act == 2) {
;               *reinterpret_cast<unsigned*>(reinterpret_cast<unsigned char*>(dst) + (size_t)t * 2048 + (EPI_F(ai, m) - cofs)) =
;                   pk4_u8(v[0], v[1], v[2], v[3]);
	v_cvt_u32_f32_sdwa v46, v46 dst_sel:WORD_1 dst_unused:UNUSED_PAD src0_sel:DWORD
	v_cvt_u32_f32_sdwa v47, v47 dst_sel:BYTE_3 dst_unused:UNUSED_PAD src0_sel:DWORD
	v_lshl_or_b32 v180, v45, 8, v44
	v_or3_b32 v180, v180, v46, v47
	v_pk_mul_f32 v[40:41], v[40:41], v[140:141] op_sel_hi:[1,0]
	v_pk_mul_f32 v[42:43], v[42:43], v[140:141] op_sel_hi:[1,0]
	v_mul_f32_e32 v40, 0xbfb8aa3b, v40
	v_mul_f32_e32 v41, 0xbfb8aa3b, v41
	v_mul_f32_e32 v42, 0xbfb8aa3b, v42
	v_mul_f32_e32 v43, 0xbfb8aa3b, v43
	v_exp_f32_e32 v40, v40
	v_exp_f32_e32 v41, v41
	v_exp_f32_e32 v42, v42
	v_exp_f32_e32 v43, v43
	v_add_f32_e32 v40, 1.0, v40
	v_add_f32_e32 v41, 1.0, v41
	v_add_f32_e32 v42, 1.0, v42
	v_add_f32_e32 v43, 1.0, v43
	v_rcp_f32_e64 v40, v40 clamp
	v_rcp_f32_e64 v41, v41 clamp
	v_rcp_f32_e64 v42, v42 clamp
	v_rcp_f32_e64 v43, v43 clamp
	v_mul_f32_e32 v40, 0x437f0000, v40
	v_mul_f32_e32 v41, 0x437f0000, v41
	v_mul_f32_e32 v42, 0x437f0000, v42
	v_mul_f32_e32 v43, 0x437f0000, v43
	v_rndne_f32_e32 v40, v40
	v_rndne_f32_e32 v41, v41
	v_rndne_f32_e32 v42, v42
	v_rndne_f32_e32 v43, v43
	v_cvt_u32_f32_e32 v40, v40
	v_cvt_u32_f32_e32 v41, v41
	v_cvt_u32_f32_sdwa v42, v42 dst_sel:WORD_1 dst_unused:UNUSED_PAD src0_sel:DWORD
	v_cvt_u32_f32_sdwa v43, v43 dst_sel:BYTE_3 dst_unused:UNUSED_PAD src0_sel:DWORD
	v_lshl_or_b32 v181, v41, 8, v40
	v_or3_b32 v181, v181, v42, v43
	v_pk_mul_f32 v[36:37], v[36:37], v[140:141] op_sel_hi:[1,0]
	v_pk_mul_f32 v[38:39], v[38:39], v[140:141] op_sel_hi:[1,0]
	v_mul_f32_e32 v36, 0xbfb8aa3b, v36
	v_mul_f32_e32 v37, 0xbfb8aa3b, v37
	v_mul_f32_e32 v38, 0xbfb8aa3b, v38
	v_mul_f32_e32 v39, 0xbfb8aa3b, v39
	v_exp_f32_e32 v36, v36
	v_exp_f32_e32 v37, v37
	v_exp_f32_e32 v38, v38
	v_exp_f32_e32 v39, v39
	v_add_f32_e32 v36, 1.0, v36
	v_add_f32_e32 v37, 1.0, v37
	v_add_f32_e32 v38, 1.0, v38
	v_add_f32_e32 v39, 1.0, v39
	v_rcp_f32_e64 v36, v36 clamp
	v_rcp_f32_e64 v37, v37 clamp
	v_rcp_f32_e64 v38, v38 clamp
	v_rcp_f32_e64 v39, v39 clamp
	v_mul_f32_e32 v36, 0x437f0000, v36
	v_mul_f32_e32 v37, 0x437f0000, v37
	v_mul_f32_e32 v38, 0x437f0000, v38
	v_mul_f32_e32 v39, 0x437f0000, v39
	v_rndne_f32_e32 v36, v36
	v_rndne_f32_e32 v37, v37
	v_rndne_f32_e32 v38, v38
	v_rndne_f32_e32 v39, v39
	v_cvt_u32_f32_e32 v36, v36
	v_cvt_u32_f32_e32 v37, v37
	v_cvt_u32_f32_sdwa v38, v38 dst_sel:WORD_1 dst_unused:UNUSED_PAD src0_sel:DWORD
	v_cvt_u32_f32_sdwa v39, v39 dst_sel:BYTE_3 dst_unused:UNUSED_PAD src0_sel:DWORD
	v_lshl_or_b32 v182, v37, 8, v36
	v_or3_b32 v182, v182, v38, v39
	v_pk_mul_f32 v[32:33], v[32:33], v[140:141] op_sel_hi:[1,0]
	v_pk_mul_f32 v[34:35], v[34:35], v[140:141] op_sel_hi:[1,0]
	v_mul_f32_e32 v32, 0xbfb8aa3b, v32
	v_mul_f32_e32 v33, 0xbfb8aa3b, v33
	v_mul_f32_e32 v34, 0xbfb8aa3b, v34
	v_mul_f32_e32 v35, 0xbfb8aa3b, v35
	v_exp_f32_e32 v32, v32
	v_exp_f32_e32 v33, v33
	v_exp_f32_e32 v34, v34
	v_exp_f32_e32 v35, v35
	v_add_f32_e32 v32, 1.0, v32
	v_add_f32_e32 v33, 1.0, v33
	v_add_f32_e32 v34, 1.0, v34
	v_add_f32_e32 v35, 1.0, v35
	v_rcp_f32_e64 v32, v32 clamp
	v_rcp_f32_e64 v33, v33 clamp
	v_rcp_f32_e64 v34, v34 clamp
	v_rcp_f32_e64 v35, v35 clamp
	v_mul_f32_e32 v32, 0x437f0000, v32
	v_mul_f32_e32 v33, 0x437f0000, v33
	v_mul_f32_e32 v34, 0x437f0000, v34
	v_mul_f32_e32 v35, 0x437f0000, v35
	v_rndne_f32_e32 v32, v32
	v_rndne_f32_e32 v33, v33
	v_rndne_f32_e32 v34, v34
	v_rndne_f32_e32 v35, v35
	v_cvt_u32_f32_e32 v32, v32
	v_cvt_u32_f32_e32 v33, v33
	v_cvt_u32_f32_sdwa v34, v34 dst_sel:WORD_1 dst_unused:UNUSED_PAD src0_sel:DWORD
	v_cvt_u32_f32_sdwa v35, v35 dst_sel:BYTE_3 dst_unused:UNUSED_PAD src0_sel:DWORD
	v_lshl_or_b32 v183, v33, 8, v32
	v_or3_b32 v183, v183, v34, v35
	s_nop 1
	v_permlane16_swap_b32 v180, v181
	v_permlane16_swap_b32 v182, v183
	s_nop 1
	v_permlane32_swap_b32 v180, v182
	v_permlane32_swap_b32 v181, v183
	global_store_dwordx4 v150, v[180:183], s[66:67] offset:128
	s_waitcnt vmcnt(14)
	v_pk_mul_f32 v[28:29], v[28:29], v[142:143] op_sel_hi:[1,0]
	v_pk_mul_f32 v[30:31], v[30:31], v[142:143] op_sel_hi:[1,0]
	v_mul_f32_e32 v28, 0xbfb8aa3b, v28
	v_mul_f32_e32 v29, 0xbfb8aa3b, v29
	v_mul_f32_e32 v30, 0xbfb8aa3b, v30
	v_mul_f32_e32 v31, 0xbfb8aa3b, v31
	v_exp_f32_e32 v28, v28
	v_exp_f32_e32 v29, v29
	v_exp_f32_e32 v30, v30
	v_exp_f32_e32 v31, v31
	v_add_f32_e32 v28, 1.0, v28
	v_add_f32_e32 v29, 1.0, v29
	v_add_f32_e32 v30, 1.0, v30
	v_add_f32_e32 v31, 1.0, v31
	v_rcp_f32_e64 v28, v28 clamp
	v_rcp_f32_e64 v29, v29 clamp
	v_rcp_f32_e64 v30, v30 clamp
	v_rcp_f32_e64 v31, v31 clamp
	v_mul_f32_e32 v28, 0x437f0000, v28
	v_mul_f32_e32 v29, 0x437f0000, v29
	v_mul_f32_e32 v30, 0x437f0000, v30
	v_mul_f32_e32 v31, 0x437f0000, v31
	v_rndne_f32_e32 v28, v28
	v_rndne_f32_e32 v29, v29
	v_rndne_f32_e32 v30, v30
	v_rndne_f32_e32 v31, v31
	v_cvt_u32_f32_e32 v28, v28
	v_cvt_u32_f32_e32 v29, v29
	v_cvt_u32_f32_sdwa v30, v30 dst_sel:WORD_1 dst_unused:UNUSED_PAD src0_sel:DWORD
	v_cvt_u32_f32_sdwa v31, v31 dst_sel:BYTE_3 dst_unused:UNUSED_PAD src0_sel:DWORD
	v_lshl_or_b32 v184, v29, 8, v28
	v_or3_b32 v184, v184, v30, v31
	v_pk_mul_f32 v[24:25], v[24:25], v[142:143] op_sel_hi:[1,0]
	v_pk_mul_f32 v[26:27], v[26:27], v[142:143] op_sel_hi:[1,0]
	v_mul_f32_e32 v24, 0xbfb8aa3b, v24
	v_mul_f32_e32 v25, 0xbfb8aa3b, v25
	v_mul_f32_e32 v26, 0xbfb8aa3b, v26
	v_mul_f32_e32 v27, 0xbfb8aa3b, v27
	v_exp_f32_e32 v24, v24
	v_exp_f32_e32 v25, v25
	v_exp_f32_e32 v26, v26
	v_exp_f32_e32 v27, v27
	v_add_f32_e32 v24, 1.0, v24
	v_add_f32_e32 v25, 1.0, v25
	v_add_f32_e32 v26, 1.0, v26
	v_add_f32_e32 v27, 1.0, v27
	v_rcp_f32_e64 v24, v24 clamp
	v_rcp_f32_e64 v25, v25 clamp
	v_rcp_f32_e64 v26, v26 clamp
	v_rcp_f32_e64 v27, v27 clamp
	v_mul_f32_e32 v24, 0x437f0000, v24
	v_mul_f32_e32 v25, 0x437f0000, v25
; __device__ void phase1(const Params& p) {
;     ...
;         const int t = EPI_T(bj, n);
;         const float r = rs[t];
;         u16* drow = dst + (size_t)t * ld - cofs;
;         #pragma unroll
;         for (int ai = 0; ai < 2; ++ai)
;           #pragma unroll
;           for (int m = 0; m < 4; ++m) {
;             float v[4];
;             #pragma unroll
;             for (int j = 0; j < 4; ++j) {
;               v[j] = acc[ai][bj][m][n][j] * r;
;               if (act == 2) v[j] = sigm(v[j]);
;             }
;             if (act == 2) {
;               *reinterpret_cast<unsigned*>(reinterpret_cast<unsigned char*>(dst) + (size_t)t * 2048 + (EPI_F(ai, m) - cofs)) =
;                   pk4_u8(v[0], v[1], v[2], v[3]);
	v_mul_f32_e32 v26, 0x437f0000, v26
	v_mul_f32_e32 v27, 0x437f0000, v27
	v_rndne_f32_e32 v24, v24
	v_rndne_f32_e32 v25, v25
	v_rndne_f32_e32 v26, v26
	v_rndne_f32_e32 v27, v27
	v_cvt_u32_f32_e32 v24, v24
	v_cvt_u32_f32_e32 v25, v25
	v_cvt_u32_f32_sdwa v26, v26 dst_sel:WORD_1 dst_unused:UNUSED_PAD src0_sel:DWORD
	v_cvt_u32_f32_sdwa v27, v27 dst_sel:BYTE_3 dst_unused:UNUSED_PAD src0_sel:DWORD
	v_lshl_or_b32 v185, v25, 8, v24
	v_or3_b32 v185, v185, v26, v27
	v_pk_mul_f32 v[20:21], v[20:21], v[142:143] op_sel_hi:[1,0]
	v_pk_mul_f32 v[22:23], v[22:23], v[142:143] op_sel_hi:[1,0]
	v_mul_f32_e32 v20, 0xbfb8aa3b, v20
	v_mul_f32_e32 v21, 0xbfb8aa3b, v21
	v_mul_f32_e32 v22, 0xbfb8aa3b, v22
	v_mul_f32_e32 v23, 0xbfb8aa3b, v23
	v_exp_f32_e32 v20, v20
	v_exp_f32_e32 v21, v21
	v_exp_f32_e32 v22, v22
	v_exp_f32_e32 v23, v23
	v_add_f32_e32 v20, 1.0, v20
	v_add_f32_e32 v21, 1.0, v21
	v_add_f32_e32 v22, 1.0, v22
	v_add_f32_e32 v23, 1.0, v23
	v_rcp_f32_e64 v20, v20 clamp
	v_rcp_f32_e64 v21, v21 clamp
	v_rcp_f32_e64 v22, v22 clamp
	v_rcp_f32_e64 v23, v23 clamp
	v_mul_f32_e32 v20, 0x437f0000, v20
	v_mul_f32_e32 v21, 0x437f0000, v21
	v_mul_f32_e32 v22, 0x437f0000, v22
	v_mul_f32_e32 v23, 0x437f0000, v23
	v_rndne_f32_e32 v20, v20
	v_rndne_f32_e32 v21, v21
	v_rndne_f32_e32 v22, v22
	v_rndne_f32_e32 v23, v23
	v_cvt_u32_f32_e32 v20, v20
	v_cvt_u32_f32_e32 v21, v21
	v_cvt_u32_f32_sdwa v22, v22 dst_sel:WORD_1 dst_unused:UNUSED_PAD src0_sel:DWORD
	v_cvt_u32_f32_sdwa v23, v23 dst_sel:BYTE_3 dst_unused:UNUSED_PAD src0_sel:DWORD
	v_lshl_or_b32 v186, v21, 8, v20
	v_or3_b32 v186, v186, v22, v23
	v_pk_mul_f32 v[16:17], v[16:17], v[142:143] op_sel_hi:[1,0]
	v_pk_mul_f32 v[18:19], v[18:19], v[142:143] op_sel_hi:[1,0]
	v_mul_f32_e32 v16, 0xbfb8aa3b, v16
	v_mul_f32_e32 v17, 0xbfb8aa3b, v17
	v_mul_f32_e32 v18, 0xbfb8aa3b, v18
	v_mul_f32_e32 v19, 0xbfb8aa3b, v19
	v_exp_f32_e32 v16, v16
	v_exp_f32_e32 v17, v17
	v_exp_f32_e32 v18, v18
	v_exp_f32_e32 v19, v19
	v_add_f32_e32 v16, 1.0, v16
	v_add_f32_e32 v17, 1.0, v17
	v_add_f32_e32 v18, 1.0, v18
	v_add_f32_e32 v19, 1.0, v19
	v_rcp_f32_e64 v16, v16 clamp
	v_rcp_f32_e64 v17, v17 clamp
	v_rcp_f32_e64 v18, v18 clamp
	v_rcp_f32_e64 v19, v19 clamp
	v_mul_f32_e32 v16, 0x437f0000, v16
	v_mul_f32_e32 v17, 0x437f0000, v17
	v_mul_f32_e32 v18, 0x437f0000, v18
	v_mul_f32_e32 v19, 0x437f0000, v19
	v_rndne_f32_e32 v16, v16
	v_rndne_f32_e32 v17, v17
	v_rndne_f32_e32 v18, v18
	v_rndne_f32_e32 v19, v19
	v_cvt_u32_f32_e32 v16, v16
	v_cvt_u32_f32_e32 v17, v17
	v_cvt_u32_f32_sdwa v18, v18 dst_sel:WORD_1 dst_unused:UNUSED_PAD src0_sel:DWORD
	v_cvt_u32_f32_sdwa v19, v19 dst_sel:BYTE_3 dst_unused:UNUSED_PAD src0_sel:DWORD
	v_lshl_or_b32 v187, v17, 8, v16
	v_or3_b32 v187, v187, v18, v19
	s_nop 1
	v_permlane16_swap_b32 v184, v185
	v_permlane16_swap_b32 v186, v187
	s_nop 1
	v_permlane32_swap_b32 v184, v186
	v_permlane32_swap_b32 v185, v187
	global_store_dwordx4 v151, v[184:187], s[66:67]
	v_pk_mul_f32 v[12:13], v[12:13], v[142:143] op_sel_hi:[1,0]
	v_pk_mul_f32 v[14:15], v[14:15], v[142:143] op_sel_hi:[1,0]
	v_mul_f32_e32 v12, 0xbfb8aa3b, v12
	v_mul_f32_e32 v13, 0xbfb8aa3b, v13
	v_mul_f32_e32 v14, 0xbfb8aa3b, v14
	v_mul_f32_e32 v15, 0xbfb8aa3b, v15
	v_exp_f32_e32 v12, v12
	v_exp_f32_e32 v13, v13
	v_exp_f32_e32 v14, v14
	v_exp_f32_e32 v15, v15
	v_add_f32_e32 v12, 1.0, v12
	v_add_f32_e32 v13, 1.0, v13
	v_add_f32_e32 v14, 1.0, v14
	v_add_f32_e32 v15, 1.0, v15
	v_rcp_f32_e64 v12, v12 clamp
	v_rcp_f32_e64 v13, v13 clamp
	v_rcp_f32_e64 v14, v14 clamp
	v_rcp_f32_e64 v15, v15 clamp
	v_mul_f32_e32 v12, 0x437f0000, v12
	v_mul_f32_e32 v13, 0x437f0000, v13
	v_mul_f32_e32 v14, 0x437f0000, v14
	v_mul_f32_e32 v15, 0x437f0000, v15
	v_rndne_f32_e32 v12, v12
	v_rndne_f32_e32 v13, v13
	v_rndne_f32_e32 v14, v14
	v_rndne_f32_e32 v15, v15
	v_cvt_u32_f32_e32 v12, v12
	v_cvt_u32_f32_e32 v13, v13
	v_cvt_u32_f32_sdwa v14, v14 dst_sel:WORD_1 dst_unused:UNUSED_PAD src0_sel:DWORD
	v_cvt_u32_f32_sdwa v15, v15 dst_sel:BYTE_3 dst_unused:UNUSED_PAD src0_sel:DWORD
	v_lshl_or_b32 v188, v13, 8, v12
	v_or3_b32 v188, v188, v14, v15
	v_pk_mul_f32 v[8:9], v[8:9], v[142:143] op_sel_hi:[1,0]
	v_pk_mul_f32 v[10:11], v[10:11], v[142:143] op_sel_hi:[1,0]
	v_mul_f32_e32 v8, 0xbfb8aa3b, v8
	v_mul_f32_e32 v9, 0xbfb8aa3b, v9
	v_mul_f32_e32 v10, 0xbfb8aa3b, v10
	v_mul_f32_e32 v11, 0xbfb8aa3b, v11
	v_exp_f32_e32 v8, v8
	v_exp_f32_e32 v9, v9
	v_exp_f32_e32 v10, v10
	v_exp_f32_e32 v11, v11
	v_add_f32_e32 v8, 1.0, v8
	v_add_f32_e32 v9, 1.0, v9
	v_add_f32_e32 v10, 1.0, v10
	v_add_f32_e32 v11, 1.0, v11
	v_rcp_f32_e64 v8, v8 clamp
	v_rcp_f32_e64 v9, v9 clamp
	v_rcp_f32_e64 v10, v10 clamp
	v_rcp_f32_e64 v11, v11 clamp
	v_mul_f32_e32 v8, 0x437f0000, v8
	v_mul_f32_e32 v9, 0x437f0000, v9
	v_mul_f32_e32 v10, 0x437f0000, v10
	v_mul_f32_e32 v11, 0x437f0000, v11
	v_rndne_f32_e32 v8, v8
	v_rndne_f32_e32 v9, v9
	v_rndne_f32_e32 v10, v10
	v_rndne_f32_e32 v11, v11
	v_cvt_u32_f32_e32 v8, v8
	v_cvt_u32_f32_e32 v9, v9
	v_cvt_u32_f32_sdwa v10, v10 dst_sel:WORD_1 dst_unused:UNUSED_PAD src0_sel:DWORD
	v_cvt_u32_f32_sdwa v11, v11 dst_sel:BYTE_3 dst_unused:UNUSED_PAD src0_sel:DWORD
	v_lshl_or_b32 v189, v9, 8, v8
	v_or3_b32 v189, v189, v10, v11
	v_pk_mul_f32 v[4:5], v[4:5], v[142:143] op_sel_hi:[1,0]
	v_pk_mul_f32 v[6:7], v[6:7], v[142:143] op_sel_hi:[1,0]
	v_mul_f32_e32 v4, 0xbfb8aa3b, v4
	v_mul_f32_e32 v5, 0xbfb8aa3b, v5
	v_mul_f32_e32 v6, 0xbfb8aa3b, v6
	v_mul_f32_e32 v7, 0xbfb8aa3b, v7
	v_exp_f32_e32 v4, v4
	v_exp_f32_e32 v5, v5
	v_exp_f32_e32 v6, v6
	v_exp_f32_e32 v7, v7
	v_add_f32_e32 v4, 1.0, v4
	v_add_f32_e32 v5, 1.0, v5
	v_add_f32_e32 v6, 1.0, v6
	v_add_f32_e32 v7, 1.0, v7
	v_rcp_f32_e64 v4, v4 clamp
	v_rcp_f32_e64 v5, v5 clamp
; __device__ void phase1(const Params& p) {
;     ...
;               v[j] = acc[ai][bj][m][n][j] * r;
;               if (act == 2) v[j] = sigm(v[j]);
;             }
;             if (act == 2) {
;               *reinterpret_cast<unsigned*>(reinterpret_cast<unsigned char*>(dst) + (size_t)t * 2048 + (EPI_F(ai, m) - cofs)) =
;                   pk4_u8(v[0], v[1], v[2], v[3]);
;             } else {
;               v2u o; o.x = pk2(v[0], v[1]); o.y = pk2(v[2], v[3]);
;               *reinterpret_cast<v2u*>(drow + EPI_F(ai, m)) = o;
;             }
	v_rcp_f32_e64 v6, v6 clamp
	v_rcp_f32_e64 v7, v7 clamp
	v_mul_f32_e32 v4, 0x437f0000, v4
	v_mul_f32_e32 v5, 0x437f0000, v5
	v_mul_f32_e32 v6, 0x437f0000, v6
	v_mul_f32_e32 v7, 0x437f0000, v7
	v_rndne_f32_e32 v4, v4
	v_rndne_f32_e32 v5, v5
	v_rndne_f32_e32 v6, v6
	v_rndne_f32_e32 v7, v7
	v_cvt_u32_f32_e32 v4, v4
	v_cvt_u32_f32_e32 v5, v5
	v_cvt_u32_f32_sdwa v6, v6 dst_sel:WORD_1 dst_unused:UNUSED_PAD src0_sel:DWORD
	v_cvt_u32_f32_sdwa v7, v7 dst_sel:BYTE_3 dst_unused:UNUSED_PAD src0_sel:DWORD
	v_lshl_or_b32 v190, v5, 8, v4
	v_or3_b32 v190, v190, v6, v7
	v_pk_mul_f32 v[0:1], v[0:1], v[142:143] op_sel_hi:[1,0]
	v_pk_mul_f32 v[2:3], v[2:3], v[142:143] op_sel_hi:[1,0]
	v_mul_f32_e32 v0, 0xbfb8aa3b, v0
	v_mul_f32_e32 v1, 0xbfb8aa3b, v1
	v_mul_f32_e32 v2, 0xbfb8aa3b, v2
	v_mul_f32_e32 v3, 0xbfb8aa3b, v3
	v_exp_f32_e32 v0, v0
	v_exp_f32_e32 v1, v1
	v_exp_f32_e32 v2, v2
	v_exp_f32_e32 v3, v3
	v_add_f32_e32 v0, 1.0, v0
	v_add_f32_e32 v1, 1.0, v1
	v_add_f32_e32 v2, 1.0, v2
	v_add_f32_e32 v3, 1.0, v3
	v_rcp_f32_e64 v0, v0 clamp
	v_rcp_f32_e64 v1, v1 clamp
	v_rcp_f32_e64 v2, v2 clamp
	v_rcp_f32_e64 v3, v3 clamp
	v_mul_f32_e32 v0, 0x437f0000, v0
	v_mul_f32_e32 v1, 0x437f0000, v1
	v_mul_f32_e32 v2, 0x437f0000, v2
	v_mul_f32_e32 v3, 0x437f0000, v3
	v_rndne_f32_e32 v0, v0
	v_rndne_f32_e32 v1, v1
	v_rndne_f32_e32 v2, v2
	v_rndne_f32_e32 v3, v3
	v_cvt_u32_f32_e32 v0, v0
	v_cvt_u32_f32_e32 v1, v1
	v_cvt_u32_f32_sdwa v2, v2 dst_sel:WORD_1 dst_unused:UNUSED_PAD src0_sel:DWORD
	v_cvt_u32_f32_sdwa v3, v3 dst_sel:BYTE_3 dst_unused:UNUSED_PAD src0_sel:DWORD
	v_lshl_or_b32 v191, v1, 8, v0
	v_or3_b32 v191, v191, v2, v3
	s_nop 1
	v_permlane16_swap_b32 v188, v189
	v_permlane16_swap_b32 v190, v191
	s_nop 1
	v_permlane32_swap_b32 v188, v190
	v_permlane32_swap_b32 v189, v191
	global_store_dwordx4 v151, v[188:191], s[66:67] offset:128
	s_branch .LBB0_153
.Lp1e_bf16:
	s_mov_b32 s101, 0
	s_sub_i32 s24, s6, s7
	v_and_b32_e32 v145, 1, v134
	v_lshlrev_b32_e32 v146, 2, v134
	v_mad_u32_u24 v146, v145, 12, v146
	v_add3_u32 v146, v146, v135, s24
	v_mul_lo_u32 v148, v132, s70
	v_lshl_add_u32 v148, v146, 1, v148
	s_lshl_b32 s25, s70, 4
	s_lshl_b32 s71, s70, 7
	v_add_u32_e32 v149, s25, v148
	v_add_u32_e32 v150, s71, v148
	v_add_u32_e32 v151, s25, v150
	s_waitcnt vmcnt(11)
	v_pk_mul_f32 v[124:125], v[124:125], v[136:137] op_sel_hi:[1,0]
	v_pk_mul_f32 v[126:127], v[126:127], v[136:137] op_sel_hi:[1,0]
	v_pk_mul_f32 v[120:121], v[120:121], v[136:137] op_sel_hi:[1,0]
	v_pk_mul_f32 v[122:123], v[122:123], v[136:137] op_sel_hi:[1,0]
	v_pk_mul_f32 v[116:117], v[116:117], v[136:137] op_sel_hi:[1,0]
	v_pk_mul_f32 v[118:119], v[118:119], v[136:137] op_sel_hi:[1,0]
	v_pk_mul_f32 v[112:113], v[112:113], v[136:137] op_sel_hi:[1,0]
	v_pk_mul_f32 v[114:115], v[114:115], v[136:137] op_sel_hi:[1,0]
	v_pk_mul_f32 v[108:109], v[108:109], v[136:137] op_sel_hi:[1,0]
	v_pk_mul_f32 v[110:111], v[110:111], v[136:137] op_sel_hi:[1,0]
	v_pk_mul_f32 v[104:105], v[104:105], v[136:137] op_sel_hi:[1,0]
	v_pk_mul_f32 v[106:107], v[106:107], v[136:137] op_sel_hi:[1,0]
	v_pk_mul_f32 v[100:101], v[100:101], v[136:137] op_sel_hi:[1,0]
	v_pk_mul_f32 v[102:103], v[102:103], v[136:137] op_sel_hi:[1,0]
	v_pk_mul_f32 v[96:97], v[96:97], v[136:137] op_sel_hi:[1,0]
	v_pk_mul_f32 v[98:99], v[98:99], v[136:137] op_sel_hi:[1,0]
	v_cvt_pk_bf16_f32 v124, v124, v125
	v_cvt_pk_bf16_f32 v125, v126, v127
	v_cvt_pk_bf16_f32 v126, v120, v121
	v_cvt_pk_bf16_f32 v127, v122, v123
	v_cvt_pk_bf16_f32 v116, v116, v117
	v_cvt_pk_bf16_f32 v117, v118, v119
	v_cvt_pk_bf16_f32 v118, v112, v113
	v_cvt_pk_bf16_f32 v119, v114, v115
	v_cvt_pk_bf16_f32 v108, v108, v109
	v_cvt_pk_bf16_f32 v109, v110, v111
	v_cvt_pk_bf16_f32 v110, v104, v105
	v_cvt_pk_bf16_f32 v111, v106, v107
	v_cvt_pk_bf16_f32 v100, v100, v101
	v_cvt_pk_bf16_f32 v101, v102, v103
	v_cvt_pk_bf16_f32 v102, v96, v97
	v_cvt_pk_bf16_f32 v103, v98, v99
	s_nop 1
	v_permlane16_swap_b32 v124, v126
	v_permlane16_swap_b32 v125, v127
	v_permlane16_swap_b32 v116, v118
	v_permlane16_swap_b32 v117, v119
	v_permlane16_swap_b32 v108, v110
	v_permlane16_swap_b32 v109, v111
	v_permlane16_swap_b32 v100, v102
	v_permlane16_swap_b32 v101, v103
	global_store_dwordx4 v148, v[124:127], s[66:67]
	global_store_dwordx4 v148, v[116:119], s[66:67] offset:64
	global_store_dwordx4 v148, v[108:111], s[66:67] offset:256
	global_store_dwordx4 v148, v[100:103], s[66:67] offset:320
	s_waitcnt vmcnt(14)
; __device__ void phase1(const Params& p) {
;     ...
;             } else {
;               v2u o; o.x = pk2(v[0], v[1]); o.y = pk2(v[2], v[3]);
;               *reinterpret_cast<v2u*>(drow + EPI_F(ai, m)) = o;
;             }
	v_pk_mul_f32 v[92:93], v[92:93], v[138:139] op_sel_hi:[1,0]
	v_pk_mul_f32 v[94:95], v[94:95], v[138:139] op_sel_hi:[1,0]
	v_pk_mul_f32 v[88:89], v[88:89], v[138:139] op_sel_hi:[1,0]
	v_pk_mul_f32 v[90:91], v[90:91], v[138:139] op_sel_hi:[1,0]
	v_pk_mul_f32 v[84:85], v[84:85], v[138:139] op_sel_hi:[1,0]
	v_pk_mul_f32 v[86:87], v[86:87], v[138:139] op_sel_hi:[1,0]
	v_pk_mul_f32 v[80:81], v[80:81], v[138:139] op_sel_hi:[1,0]
	v_pk_mul_f32 v[82:83], v[82:83], v[138:139] op_sel_hi:[1,0]
	v_pk_mul_f32 v[76:77], v[76:77], v[138:139] op_sel_hi:[1,0]
	v_pk_mul_f32 v[78:79], v[78:79], v[138:139] op_sel_hi:[1,0]
	v_pk_mul_f32 v[72:73], v[72:73], v[138:139] op_sel_hi:[1,0]
	v_pk_mul_f32 v[74:75], v[74:75], v[138:139] op_sel_hi:[1,0]
	v_pk_mul_f32 v[68:69], v[68:69], v[138:139] op_sel_hi:[1,0]
	v_pk_mul_f32 v[70:71], v[70:71], v[138:139] op_sel_hi:[1,0]
	v_pk_mul_f32 v[64:65], v[64:65], v[138:139] op_sel_hi:[1,0]
	v_pk_mul_f32 v[66:67], v[66:67], v[138:139] op_sel_hi:[1,0]
	v_cvt_pk_bf16_f32 v92, v92, v93
	v_cvt_pk_bf16_f32 v93, v94, v95
	v_cvt_pk_bf16_f32 v94, v88, v89
	v_cvt_pk_bf16_f32 v95, v90, v91
	v_cvt_pk_bf16_f32 v84, v84, v85
	v_cvt_pk_bf16_f32 v85, v86, v87
	v_cvt_pk_bf16_f32 v86, v80, v81
	v_cvt_pk_bf16_f32 v87, v82, v83
	v_cvt_pk_bf16_f32 v76, v76, v77
	v_cvt_pk_bf16_f32 v77, v78, v79
	v_cvt_pk_bf16_f32 v78, v72, v73
	v_cvt_pk_bf16_f32 v79, v74, v75
	v_cvt_pk_bf16_f32 v68, v68, v69
	v_cvt_pk_bf16_f32 v69, v70, v71
	v_cvt_pk_bf16_f32 v70, v64, v65
	v_cvt_pk_bf16_f32 v71, v66, v67
	s_nop 1
	v_permlane16_swap_b32 v92, v94
	v_permlane16_swap_b32 v93, v95
	v_permlane16_swap_b32 v84, v86
	v_permlane16_swap_b32 v85, v87
	v_permlane16_swap_b32 v76, v78
	v_permlane16_swap_b32 v77, v79
	v_permlane16_swap_b32 v68, v70
	v_permlane16_swap_b32 v69, v71
	global_store_dwordx4 v149, v[92:95], s[66:67]
	global_store_dwordx4 v149, v[84:87], s[66:67] offset:64
	global_store_dwordx4 v149, v[76:79], s[66:67] offset:256
	global_store_dwordx4 v149, v[68:71], s[66:67] offset:320
	s_waitcnt vmcnt(17)
	v_pk_mul_f32 v[60:61], v[60:61], v[140:141] op_sel_hi:[1,0]
	v_pk_mul_f32 v[62:63], v[62:63], v[140:141] op_sel_hi:[1,0]
	v_pk_mul_f32 v[56:57], v[56:57], v[140:141] op_sel_hi:[1,0]
	v_pk_mul_f32 v[58:59], v[58:59], v[140:141] op_sel_hi:[1,0]
	v_pk_mul_f32 v[52:53], v[52:53], v[140:141] op_sel_hi:[1,0]
	v_pk_mul_f32 v[54:55], v[54:55], v[140:141] op_sel_hi:[1,0]
	v_pk_mul_f32 v[48:49], v[48:49], v[140:141] op_sel_hi:[1,0]
	v_pk_mul_f32 v[50:51], v[50:51], v[140:141] op_sel_hi:[1,0]
	v_pk_mul_f32 v[44:45], v[44:45], v[140:141] op_sel_hi:[1,0]
	v_pk_mul_f32 v[46:47], v[46:47], v[140:141] op_sel_hi:[1,0]
	v_pk_mul_f32 v[40:41], v[40:41], v[140:141] op_sel_hi:[1,0]
	v_pk_mul_f32 v[42:43], v[42:43], v[140:141] op_sel_hi:[1,0]
	v_pk_mul_f32 v[36:37], v[36:37], v[140:141] op_sel_hi:[1,0]
	v_pk_mul_f32 v[38:39], v[38:39], v[140:141] op_sel_hi:[1,0]
	v_pk_mul_f32 v[32:33], v[32:33], v[140:141] op_sel_hi:[1,0]
	v_pk_mul_f32 v[34:35], v[34:35], v[140:141] op_sel_hi:[1,0]
	v_cvt_pk_bf16_f32 v60, v60, v61
	v_cvt_pk_bf16_f32 v61, v62, v63
	v_cvt_pk_bf16_f32 v62, v56, v57
	v_cvt_pk_bf16_f32 v63, v58, v59
	v_cvt_pk_bf16_f32 v52, v52, v53
	v_cvt_pk_bf16_f32 v53, v54, v55
	v_cvt_pk_bf16_f32 v54, v48, v49
	v_cvt_pk_bf16_f32 v55, v50, v51
	v_cvt_pk_bf16_f32 v44, v44, v45
	v_cvt_pk_bf16_f32 v45, v46, v47
	v_cvt_pk_bf16_f32 v46, v40, v41
	v_cvt_pk_bf16_f32 v47, v42, v43
	v_cvt_pk_bf16_f32 v36, v36, v37
	v_cvt_pk_bf16_f32 v37, v38, v39
	v_cvt_pk_bf16_f32 v38, v32, v33
	v_cvt_pk_bf16_f32 v39, v34, v35
	s_nop 1
	v_permlane16_swap_b32 v60, v62
	v_permlane16_swap_b32 v61, v63
	v_permlane16_swap_b32 v52, v54
	v_permlane16_swap_b32 v53, v55
	v_permlane16_swap_b32 v44, v46
	v_permlane16_swap_b32 v45, v47
	v_permlane16_swap_b32 v36, v38
	v_permlane16_swap_b32 v37, v39
	global_store_dwordx4 v150, v[60:63], s[66:67]
	global_store_dwordx4 v150, v[52:55], s[66:67] offset:64
	global_store_dwordx4 v150, v[44:47], s[66:67] offset:256
	global_store_dwordx4 v150, v[36:39], s[66:67] offset:320
	s_waitcnt vmcnt(20)
	v_pk_mul_f32 v[28:29], v[28:29], v[142:143] op_sel_hi:[1,0]
	v_pk_mul_f32 v[30:31], v[30:31], v[142:143] op_sel_hi:[1,0]
	v_pk_mul_f32 v[24:25], v[24:25], v[142:143] op_sel_hi:[1,0]
	v_pk_mul_f32 v[26:27], v[26:27], v[142:143] op_sel_hi:[1,0]
	v_pk_mul_f32 v[20:21], v[20:21], v[142:143] op_sel_hi:[1,0]
	v_pk_mul_f32 v[22:23], v[22:23], v[142:143] op_sel_hi:[1,0]
	v_pk_mul_f32 v[16:17], v[16:17], v[142:143] op_sel_hi:[1,0]
	v_pk_mul_f32 v[18:19], v[18:19], v[142:143] op_sel_hi:[1,0]
	v_pk_mul_f32 v[12:13], v[12:13], v[142:143] op_sel_hi:[1,0]
	v_pk_mul_f32 v[14:15], v[14:15], v[142:143] op_sel_hi:[1,0]
	v_pk_mul_f32 v[8:9], v[8:9], v[142:143] op_sel_hi:[1,0]
	v_pk_mul_f32 v[10:11], v[10:11], v[142:143] op_sel_hi:[1,0]
	v_pk_mul_f32 v[4:5], v[4:5], v[142:143] op_sel_hi:[1,0]
	v_pk_mul_f32 v[6:7], v[6:7], v[142:143] op_sel_hi:[1,0]
	v_pk_mul_f32 v[0:1], v[0:1], v[142:143] op_sel_hi:[1,0]
	v_pk_mul_f32 v[2:3], v[2:3], v[142:143] op_sel_hi:[1,0]
	v_cvt_pk_bf16_f32 v28, v28, v29
	v_cvt_pk_bf16_f32 v29, v30, v31
	v_cvt_pk_bf16_f32 v30, v24, v25
	v_cvt_pk_bf16_f32 v31, v26, v27
	v_cvt_pk_bf16_f32 v20, v20, v21
	v_cvt_pk_bf16_f32 v21, v22, v23
	v_cvt_pk_bf16_f32 v22, v16, v17
	v_cvt_pk_bf16_f32 v23, v18, v19
	v_cvt_pk_bf16_f32 v12, v12, v13
	v_cvt_pk_bf16_f32 v13, v14, v15
	v_cvt_pk_bf16_f32 v14, v8, v9
	v_cvt_pk_bf16_f32 v15, v10, v11
	v_cvt_pk_bf16_f32 v4, v4, v5
	v_cvt_pk_bf16_f32 v5, v6, v7
	v_cvt_pk_bf16_f32 v6, v0, v1
	v_cvt_pk_bf16_f32 v7, v2, v3
	s_nop 1
	v_permlane16_swap_b32 v28, v30
	v_permlane16_swap_b32 v29, v31
	v_permlane16_swap_b32 v20, v22
	v_permlane16_swap_b32 v21, v23
	v_permlane16_swap_b32 v12, v14
	v_permlane16_swap_b32 v13, v15
	v_permlane16_swap_b32 v4, v6
	v_permlane16_swap_b32 v5, v7
	global_store_dwordx4 v151, v[28:31], s[66:67]
	global_store_dwordx4 v151, v[20:23], s[66:67] offset:64
	global_store_dwordx4 v151, v[12:15], s[66:67] offset:256
	global_store_dwordx4 v151, v[4:7], s[66:67] offset:320
	s_branch .LBB0_153

; __global__ void __launch_bounds__(512, 2) fwd_megakernel(Params p) {
;   cg::grid_group grid = cg::this_grid();
	.amdhsa_kernel _Z14fwd_megakernel6Params
		.amdhsa_group_segment_fixed_size 131088
		.amdhsa_private_segment_fixed_size 0
		.amdhsa_kernarg_size 432
		.amdhsa_user_sgpr_count 2
		.amdhsa_user_sgpr_dispatch_ptr 0
		.amdhsa_user_sgpr_queue_ptr 0
		.amdhsa_user_sgpr_kernarg_segment_ptr 1
		.amdhsa_user_sgpr_dispatch_id 0
		.amdhsa_user_sgpr_kernarg_preload_length 0
		.amdhsa_user_sgpr_kernarg_preload_offset 0
		.amdhsa_user_sgpr_private_segment_size 0
		.amdhsa_uses_dynamic_stack 0
		.amdhsa_enable_private_segment 0
		.amdhsa_system_sgpr_workgroup_id_x 1
		.amdhsa_system_sgpr_workgroup_id_y 0
		.amdhsa_system_sgpr_workgroup_id_z 0
		.amdhsa_system_sgpr_workgroup_info 0
		.amdhsa_system_vgpr_workitem_id 2
		.amdhsa_next_free_vgpr 255
		.amdhsa_next_free_sgpr 102
		.amdhsa_accum_offset 256
		.amdhsa_reserve_vcc 1
		.amdhsa_float_round_mode_32 0
		.amdhsa_float_round_mode_16_64 0
		.amdhsa_float_denorm_mode_32 3
		.amdhsa_float_denorm_mode_16_64 3
		.amdhsa_dx10_clamp 1
		.amdhsa_ieee_mode 1
		.amdhsa_fp16_overflow 0
		.amdhsa_tg_split 0
		.amdhsa_exception_fp_ieee_invalid_op 0
		.amdhsa_exception_fp_denorm_src 0
		.amdhsa_exception_fp_ieee_div_zero 0
		.amdhsa_exception_fp_ieee_overflow 0
		.amdhsa_exception_fp_ieee_underflow 0
		.amdhsa_exception_fp_ieee_inexact 0
		.amdhsa_exception_int_div_zero 0
	.end_amdhsa_kernel

; __global__ void __launch_bounds__(512, 2) fwd_megakernel(Params p) {
;   cg::grid_group grid = cg::this_grid();
amdhsa.kernels:
  - .agpr_count:     0
    .args:
      - .offset:         0
        .size:           176
        .value_kind:     by_value
      - .offset:         176
        .size:           4
        .value_kind:     hidden_block_count_x
      - .offset:         180
        .size:           4
        .value_kind:     hidden_block_count_y
      - .offset:         184
        .size:           4
        .value_kind:     hidden_block_count_z
      - .offset:         188
        .size:           2
        .value_kind:     hidden_group_size_x
      - .offset:         190
        .size:           2
        .value_kind:     hidden_group_size_y
      - .offset:         192
        .size:           2
        .value_kind:     hidden_group_size_z
      - .offset:         194
        .size:           2
        .value_kind:     hidden_remainder_x
      - .offset:         196
        .size:           2
        .value_kind:     hidden_remainder_y
      - .offset:         198
        .size:           2
        .value_kind:     hidden_remainder_z
      - .offset:         216
        .size:           8
        .value_kind:     hidden_global_offset_x
      - .offset:         224
        .size:           8
        .value_kind:     hidden_global_offset_y
      - .offset:         232
        .size:           8
        .value_kind:     hidden_global_offset_z
      - .offset:         240
        .size:           2
        .value_kind:     hidden_grid_dims
      - .offset:         264
        .size:           8
        .value_kind:     hidden_multigrid_sync_arg
    .group_segment_fixed_size: 131088
    .kernarg_segment_align: 8
    .kernarg_segment_size: 432
    .language:       OpenCL C
    .language_version:
      - 2
      - 0
    .max_flat_workgroup_size: 512
    .name:           _Z14fwd_megakernel6Params
    .private_segment_fixed_size: 0
    .sgpr_count:     108
    .sgpr_spill_count: 4
    .symbol:         _Z14fwd_megakernel6Params.kd
    .uniform_work_group_size: 1
    .uses_dynamic_stack: false
    .vgpr_count:     255
    .vgpr_spill_count: 0
    .wavefront_size: 64
